# lever 8: LRU pass-1 gate-weight fragments read in one batch per block into free registers, next block's batch issued right after the previous block's MFMAs
# speedup vs baseline: 1.0048x; 1.0002x over previous
; #define LAS __attribute__((address_space(3)))
; __device__ __forceinline__ float bf_lo(unsigned w) { return __uint_as_float(w << 16); }
; __device__ __forceinline__ float bf_hi(unsigned w) { return __uint_as_float(w & 0xffff0000u); }
; #define LDS_WAIT() asm volatile("s_waitcnt lgkmcnt(0)" ::: "memory")
; template <int PASS>
; __device__ __forceinline__ void lru_item(Frame& F, const LAS bf16* lw, const LAS float* prm, const LAS float* cwl, LAS float* xs, LAS unsigned char* pf, int head, int item, int nitem) {
;     ...
;     u32x4 vw[4][4];
; #pragma unroll
;     for (int k = 0; k < 4; ++k) {
;         const int rr = r - 1 + k; const bool ok = (rr >= 0) && (rr < 256);
;         const int row = t + k;
; #pragma unroll
;         for (int ks = 0; ks < 4; ++ks) { u32x4 w = *(const LAS u32x4*)(pf + row * 128 + (((2 * ks + hh) ^ ((row >> 1) & 7)) * 16)); if (!ok) w = (u32x4){0u, 0u, 0u, 0u}; vw[k][ks] = w; }
;     }
;     LDS_WAIT(); asm volatile("" ::: "memory");
;     if (nitem >= 0) lru_prefetch(F.ws, pf, lane, head, nitem);
;     float lc[2][2]; u32x4 gq[4];
;     const size_t tok = (size_t)b * SEQ + (size_t)r * 64 + col;
;     if (PASS == 2) {
; #pragma unroll
;         for (int d = 0; d < 2; ++d)
; #pragma unroll
;             for (int ct = 0; ct < 2; ++ct) lc[d][ct] = ((const float*)(F.ws + WS_LC))[(size_t)((b * 2 + d) * NQ + q) * 1024 + head * 64 + t + 32 * ct];
;     }
;     float xa[4][8];
; #pragma unroll
;     for (int ks = 0; ks < 4; ++ks) {
;         const int ch = 16 * ks + 8 * hh;
;         const f32x4 b0 = *(const LAS f32x4*)(cwl + 4 * 64 + ch), b1 = *(const LAS f32x4*)(cwl + 4 * 64 + ch + 4);
; #pragma unroll
;         for (int j = 0; j < 4; ++j) { xa[ks][j] = b0[j]; xa[ks][4 + j] = b1[j]; }
;     }
; #pragma unroll
;     for (int k = 0; k < 4; ++k)
; #pragma unroll
;         for (int ks = 0; ks < 4; ++ks) {
;             const u32x4 w = vw[k][ks]; const int ch = 16 * ks + 8 * hh;
;             const f32x4 c0 = *(const LAS f32x4*)(cwl + k * 64 + ch), c1 = *(const LAS f32x4*)(cwl + k * 64 + ch + 4);
;             xa[ks][0] += c0[0] * bf_lo(w.x); xa[ks][1] += c0[1] * bf_hi(w.x); xa[ks][2] += c0[2] * bf_lo(w.y); xa[ks][3] += c0[3] * bf_hi(w.y);
;             xa[ks][4] += c1[0] * bf_lo(w.z); xa[ks][5] += c1[1] * bf_hi(w.z); xa[ks][6] += c1[2] * bf_lo(w.w); xa[ks][7] += c1[3] * bf_hi(w.w);
;         }
.LBB0_702:
	v_add_u32_e32 v64, s18, v110
	v_cmp_gt_u32_e32 vcc, s42, v64
	v_and_b32_e32 v88, 0xffffffe0, v111
	v_add_u32_e32 v124, 0, v88
	s_waitcnt lgkmcnt(0)
	v_cndmask_b32_e32 v125, 0, v21, vcc
	v_cndmask_b32_e32 v166, 0, v20, vcc
	v_cndmask_b32_e32 v84, 0, v23, vcc
	v_cndmask_b32_e32 v85, 0, v22, vcc
	v_cndmask_b32_e32 v167, 0, v9, vcc
	v_cndmask_b32_e32 v168, 0, v8, vcc
	v_cndmask_b32_e32 v90, 0, v11, vcc
	v_cndmask_b32_e32 v91, 0, v10, vcc
	v_cndmask_b32_e32 v169, 0, v25, vcc
	v_cndmask_b32_e32 v170, 0, v24, vcc
	v_cndmask_b32_e32 v92, 0, v27, vcc
	v_cndmask_b32_e32 v93, 0, v26, vcc
	v_cndmask_b32_e32 v117, 0, v17, vcc
	v_cndmask_b32_e32 v120, 0, v16, vcc
	v_cndmask_b32_e32 v134, 0, v19, vcc
	v_cndmask_b32_e32 v135, 0, v18, vcc
	v_cmp_eq_u32_e32 vcc, s49, v64
	v_add_u32_e32 v8, 3, v64
	v_lshlrev_b32_e32 v81, 16, v30
	v_cndmask_b32_e64 v171, v63, 0, vcc
	v_cndmask_b32_e64 v172, v62, 0, vcc
	v_cndmask_b32_e64 v173, v61, 0, vcc
	v_cndmask_b32_e64 v174, v60, 0, vcc
	v_cndmask_b32_e64 v175, v47, 0, vcc
	v_cndmask_b32_e64 v176, v46, 0, vcc
	v_cndmask_b32_e64 v177, v45, 0, vcc
	v_cndmask_b32_e64 v178, v44, 0, vcc
	v_cndmask_b32_e64 v123, v55, 0, vcc
	v_cndmask_b32_e64 v179, v54, 0, vcc
	v_cndmask_b32_e64 v180, v53, 0, vcc
	v_cndmask_b32_e64 v181, v52, 0, vcc
	v_cndmask_b32_e64 v113, v39, 0, vcc
	v_cndmask_b32_e64 v115, v38, 0, vcc
	v_cndmask_b32_e64 v118, v37, 0, vcc
	v_cndmask_b32_e64 v121, v36, 0, vcc
	v_cmp_gt_u32_e32 vcc, s42, v8
	v_lshlrev_b32_e32 v80, 16, v85
	s_ashr_i32 s4, s62, 3
	v_cndmask_b32_e32 v182, 0, v59, vcc
	v_cndmask_b32_e32 v183, 0, v58, vcc
	v_cndmask_b32_e32 v184, 0, v57, vcc
	v_cndmask_b32_e32 v185, 0, v56, vcc
	v_cndmask_b32_e32 v186, 0, v43, vcc
	v_cndmask_b32_e32 v187, 0, v42, vcc
	v_cndmask_b32_e32 v188, 0, v41, vcc
	v_cndmask_b32_e32 v189, 0, v40, vcc
	v_cndmask_b32_e32 v190, 0, v51, vcc
	v_cndmask_b32_e32 v191, 0, v50, vcc
	v_cndmask_b32_e32 v192, 0, v49, vcc
	v_cndmask_b32_e32 v193, 0, v48, vcc
	v_cndmask_b32_e32 v114, 0, v35, vcc
	v_cndmask_b32_e32 v116, 0, v34, vcc
	v_cndmask_b32_e32 v119, 0, v33, vcc
	v_cndmask_b32_e32 v122, 0, v32, vcc
	ds_read_b128 v[36:39], v124 offset:39424
	ds_read_b128 v[52:55], v124 offset:39440
	ds_read_b128 v[64:67], v124 offset:39488
	ds_read_b128 v[60:63], v124 offset:39504
	ds_read_b128 v[44:47], v124 offset:39552
	ds_read_b128 v[24:27], v124 offset:39568
	ds_read_b128 v[16:19], v124 offset:39616
	ds_read_b128 v[8:11], v124 offset:39632
	ds_read_b128 v[126:129], v124 offset:38400
	ds_read_b128 v[32:35], v124 offset:38416
	ds_read_b128 v[76:79], v124 offset:38464
	ds_read_b128 v[40:43], v124 offset:38480
	ds_read_b128 v[48:51], v124 offset:38528
	ds_read_b128 v[56:59], v124 offset:38544
	ds_read_b128 v[130:133], v124 offset:38656
	ds_read_b128 v[68:71], v124 offset:38672
	ds_read_b128 v[20:23], v124 offset:38592
	ds_read_b128 v[72:75], v124 offset:38608
	s_waitcnt lgkmcnt(0)
	v_mov_b32_e32 v82, v32
	v_lshlrev_b32_e32 v32, 16, v84
	v_mov_b32_e32 v83, v68
	v_pk_mul_f32 v[158:159], v[82:83], v[80:81]
	v_and_b32_e32 v81, 0xffff0000, v30
	v_and_b32_e32 v80, 0xffff0000, v85
	v_mov_b32_e32 v68, v33
	v_pk_mul_f32 v[160:161], v[68:69], v[80:81]
	v_lshlrev_b32_e32 v33, 16, v31
	v_mov_b32_e32 v68, v34
	v_mov_b32_e32 v69, v70
	v_pk_mul_f32 v[162:163], v[68:69], v[32:33]
	v_and_b32_e32 v69, 0xffff0000, v31
	v_and_b32_e32 v68, 0xffff0000, v84
	ds_read_b128 v[84:87], v124 offset:38720
	ds_read_b128 v[30:33], v124 offset:38736
	v_mov_b32_e32 v70, v35
	v_pk_mul_f32 v[164:165], v[70:71], v[68:69]
	v_lshlrev_b32_e32 v35, 16, v14
	v_lshlrev_b32_e32 v34, 16, v91
	v_mov_b32_e32 v68, v40
	s_waitcnt lgkmcnt(0)
	v_mov_b32_e32 v69, v30
	v_pk_mul_f32 v[104:105], v[68:69], v[34:35]
	ds_read_b128 v[68:71], v124 offset:38784
	ds_read_b128 v[80:83], v124 offset:38800
	v_and_b32_e32 v35, 0xffff0000, v14
	v_and_b32_e32 v34, 0xffff0000, v91
	v_mov_b32_e32 v30, v41
	v_pk_mul_f32 v[106:107], v[30:31], v[34:35]
	v_lshlrev_b32_e32 v31, 16, v15
	v_lshlrev_b32_e32 v30, 16, v90
	v_mov_b32_e32 v34, v42
	v_mov_b32_e32 v35, v32
	v_and_b32_e32 v15, 0xffff0000, v15
	v_and_b32_e32 v14, 0xffff0000, v90
	v_mov_b32_e32 v32, v43
	v_pk_mul_f32 v[102:103], v[34:35], v[30:31]
	v_pk_mul_f32 v[14:15], v[32:33], v[14:15]
	v_lshlrev_b32_e32 v31, 16, v6
	v_lshlrev_b32_e32 v30, 16, v93
	v_mov_b32_e32 v32, v56
	s_waitcnt lgkmcnt(0)
	v_mov_b32_e32 v33, v80
	v_pk_mul_f32 v[98:99], v[32:33], v[30:31]
	v_and_b32_e32 v31, 0xffff0000, v6
	v_and_b32_e32 v30, 0xffff0000, v93
	v_mov_b32_e32 v80, v57
	v_pk_mul_f32 v[100:101], v[80:81], v[30:31]
	v_lshlrev_b32_e32 v31, 16, v7
	v_lshlrev_b32_e32 v30, 16, v92
	v_mov_b32_e32 v32, v58
	v_mov_b32_e32 v33, v82
	v_pk_mul_f32 v[94:95], v[32:33], v[30:31]
	ds_read_b128 v[40:43], v124 offset:38848
	ds_read_b128 v[30:33], v124 offset:38864
	v_and_b32_e32 v7, 0xffff0000, v7
	v_and_b32_e32 v6, 0xffff0000, v92
	v_mov_b32_e32 v82, v59
	v_pk_mul_f32 v[96:97], v[82:83], v[6:7]
	v_lshlrev_b32_e32 v7, 16, v2
	v_lshlrev_b32_e32 v6, 16, v135
	v_mov_b32_e32 v34, v72
	s_waitcnt lgkmcnt(0)
	v_mov_b32_e32 v35, v30
	v_pk_mul_f32 v[90:91], v[34:35], v[6:7]
	v_and_b32_e32 v7, 0xffff0000, v2
	v_and_b32_e32 v6, 0xffff0000, v135
	v_mov_b32_e32 v30, v73
	v_pk_mul_f32 v[92:93], v[30:31], v[6:7]
	v_lshlrev_b32_e32 v7, 16, v3
	v_lshlrev_b32_e32 v6, 16, v134
	v_mov_b32_e32 v30, v74
	v_mov_b32_e32 v31, v32
	v_and_b32_e32 v3, 0xffff0000, v3
	v_and_b32_e32 v2, 0xffff0000, v134
	v_mov_b32_e32 v32, v75
	v_pk_mul_f32 v[6:7], v[30:31], v[6:7]
	v_pk_mul_f32 v[34:35], v[32:33], v[2:3]
	ds_read_b128 v[134:137], v124 offset:38912
	ds_read_b128 v[138:141], v124 offset:38928
	ds_read_b128 v[142:145], v124 offset:38976
	ds_read_b128 v[146:149], v124 offset:38992
	ds_read_b128 v[80:83], v124 offset:39040
	ds_read_b128 v[72:75], v124 offset:39056
	ds_read_b128 v[56:59], v124 offset:39104
	ds_read_b128 v[30:33], v124 offset:39120
	ds_read_b128 v[150:153], v124 offset:39168
	ds_read_b128 v[154:157], v124 offset:39184
	v_lshlrev_b32_e32 v2, 16, v166
	v_and_b32_e32 v3, 0xffff0000, v166
	v_pk_fma_f32 v[2:3], v[126:127], v[2:3], v[36:37]
	v_lshlrev_b32_e32 v36, 16, v28
	v_and_b32_e32 v37, 0xffff0000, v28
	v_pk_fma_f32 v[2:3], v[130:131], v[36:37], v[2:3]
	v_lshlrev_b32_e32 v36, 16, v174
	v_and_b32_e32 v37, 0xffff0000, v174
	s_waitcnt lgkmcnt(0)
; #define LAS __attribute__((address_space(3)))
; __device__ __forceinline__ float bf_lo(unsigned w) { return __uint_as_float(w << 16); }
; __device__ __forceinline__ float bf_hi(unsigned w) { return __uint_as_float(w & 0xffff0000u); }
; template <int PASS>
; __device__ __forceinline__ void lru_item(Frame& F, const LAS bf16* lw, const LAS float* prm, const LAS float* cwl, LAS float* xs, LAS unsigned char* pf, int head, int item, int nitem) {
;     ...
; #pragma unroll
;     for (int k = 0; k < 4; ++k)
; #pragma unroll
;         for (int ks = 0; ks < 4; ++ks) {
;             const u32x4 w = vw[k][ks]; const int ch = 16 * ks + 8 * hh;
;             const f32x4 c0 = *(const LAS f32x4*)(cwl + k * 64 + ch), c1 = *(const LAS f32x4*)(cwl + k * 64 + ch + 4);
;             xa[ks][0] += c0[0] * bf_lo(w.x); xa[ks][1] += c0[1] * bf_hi(w.x); xa[ks][2] += c0[2] * bf_lo(w.y); xa[ks][3] += c0[3] * bf_hi(w.y);
;             xa[ks][4] += c1[0] * bf_lo(w.z); xa[ks][5] += c1[1] * bf_hi(w.z); xa[ks][6] += c1[2] * bf_lo(w.w); xa[ks][7] += c1[3] * bf_hi(w.w);
;         }
	v_pk_fma_f32 v[2:3], v[134:135], v[36:37], v[2:3]
	v_lshlrev_b32_e32 v36, 16, v185
	v_and_b32_e32 v37, 0xffff0000, v185
	v_pk_fma_f32 v[36:37], v[150:151], v[36:37], v[2:3]
	v_lshlrev_b32_e32 v2, 16, v125
	v_and_b32_e32 v3, 0xffff0000, v125
	v_pk_fma_f32 v[2:3], v[128:129], v[2:3], v[38:39]
	v_lshlrev_b32_e32 v28, 16, v29
	v_and_b32_e32 v29, 0xffff0000, v29
	v_pk_fma_f32 v[2:3], v[132:133], v[28:29], v[2:3]
	v_lshlrev_b32_e32 v28, 16, v173
	v_and_b32_e32 v29, 0xffff0000, v173
	v_pk_fma_f32 v[2:3], v[136:137], v[28:29], v[2:3]
	v_lshlrev_b32_e32 v28, 16, v184
	v_and_b32_e32 v29, 0xffff0000, v184
	v_pk_fma_f32 v[38:39], v[152:153], v[28:29], v[2:3]
	v_lshlrev_b32_e32 v2, 16, v172
	v_lshlrev_b32_e32 v3, 16, v183
	v_mov_b32_e32 v28, v138
	v_mov_b32_e32 v29, v154
	v_pk_mul_f32 v[2:3], v[28:29], v[2:3]
	v_and_b32_e32 v29, 0xffff0000, v183
	v_and_b32_e32 v28, 0xffff0000, v172
	v_mov_b32_e32 v154, v139
	v_mov_b32_e32 v126, v158
	v_mov_b32_e32 v127, v160
	v_pk_mul_f32 v[28:29], v[154:155], v[28:29]
	v_pk_add_f32 v[52:53], v[52:53], v[126:127]
	v_mov_b32_e32 v160, v159
	v_pk_add_f32 v[52:53], v[52:53], v[160:161]
	v_mov_b32_e32 v126, v2
	v_mov_b32_e32 v127, v28
	v_pk_add_f32 v[52:53], v[52:53], v[126:127]
	v_mov_b32_e32 v28, v3
	v_pk_add_f32 v[52:53], v[52:53], v[28:29]
	v_lshlrev_b32_e32 v2, 16, v171
	v_lshlrev_b32_e32 v3, 16, v182
	v_mov_b32_e32 v28, v140
	v_mov_b32_e32 v29, v156
	v_pk_mul_f32 v[2:3], v[28:29], v[2:3]
	v_and_b32_e32 v29, 0xffff0000, v182
	v_and_b32_e32 v28, 0xffff0000, v171
	v_mov_b32_e32 v156, v141
	v_mov_b32_e32 v126, v162
	v_mov_b32_e32 v127, v164
	v_pk_mul_f32 v[28:29], v[156:157], v[28:29]
	v_pk_add_f32 v[54:55], v[54:55], v[126:127]
	v_mov_b32_e32 v164, v163
	v_pk_add_f32 v[54:55], v[54:55], v[164:165]
	v_mov_b32_e32 v126, v2
	v_mov_b32_e32 v127, v28
	v_pk_add_f32 v[54:55], v[54:55], v[126:127]
	v_mov_b32_e32 v28, v3
	ds_read_b128 v[126:129], v124 offset:39232
	ds_read_b128 v[130:133], v124 offset:39248
	v_lshlrev_b32_e32 v2, 16, v168
	v_and_b32_e32 v3, 0xffff0000, v168
	v_pk_add_f32 v[54:55], v[54:55], v[28:29]
	v_pk_fma_f32 v[2:3], v[76:77], v[2:3], v[64:65]
	v_lshlrev_b32_e32 v28, 16, v12
	v_and_b32_e32 v29, 0xffff0000, v12
	v_pk_fma_f32 v[2:3], v[84:85], v[28:29], v[2:3]
	v_lshlrev_b32_e32 v28, 16, v178
	v_and_b32_e32 v29, 0xffff0000, v178
	v_pk_fma_f32 v[2:3], v[142:143], v[28:29], v[2:3]
	v_lshlrev_b32_e32 v28, 16, v189
	v_and_b32_e32 v29, 0xffff0000, v189
	s_waitcnt lgkmcnt(0)
	v_pk_fma_f32 v[64:65], v[126:127], v[28:29], v[2:3]
	v_lshlrev_b32_e32 v2, 16, v167
	v_and_b32_e32 v3, 0xffff0000, v167
	v_pk_fma_f32 v[2:3], v[78:79], v[2:3], v[66:67]
	v_lshlrev_b32_e32 v12, 16, v13
	v_and_b32_e32 v13, 0xffff0000, v13
	v_pk_fma_f32 v[2:3], v[86:87], v[12:13], v[2:3]
	v_lshlrev_b32_e32 v12, 16, v177
	v_and_b32_e32 v13, 0xffff0000, v177
	v_pk_fma_f32 v[2:3], v[144:145], v[12:13], v[2:3]
	v_lshlrev_b32_e32 v12, 16, v188
	v_and_b32_e32 v13, 0xffff0000, v188
	v_pk_fma_f32 v[66:67], v[128:129], v[12:13], v[2:3]
	v_lshlrev_b32_e32 v2, 16, v176
	v_lshlrev_b32_e32 v3, 16, v187
	v_mov_b32_e32 v12, v146
	v_mov_b32_e32 v13, v130
	v_pk_mul_f32 v[2:3], v[12:13], v[2:3]
	v_and_b32_e32 v13, 0xffff0000, v187
	v_and_b32_e32 v12, 0xffff0000, v176
	v_mov_b32_e32 v130, v147
	v_mov_b32_e32 v28, v104
	v_mov_b32_e32 v29, v106
	v_pk_mul_f32 v[12:13], v[130:131], v[12:13]
	v_pk_add_f32 v[28:29], v[60:61], v[28:29]
	v_mov_b32_e32 v106, v105
	v_pk_add_f32 v[28:29], v[28:29], v[106:107]
	v_mov_b32_e32 v60, v2
	v_mov_b32_e32 v61, v12
	v_pk_add_f32 v[28:29], v[28:29], v[60:61]
	v_mov_b32_e32 v12, v3
	v_pk_add_f32 v[12:13], v[28:29], v[12:13]
	v_lshlrev_b32_e32 v2, 16, v175
	v_lshlrev_b32_e32 v3, 16, v186
	v_mov_b32_e32 v28, v148
	v_mov_b32_e32 v29, v132
	v_pk_mul_f32 v[2:3], v[28:29], v[2:3]
	v_and_b32_e32 v29, 0xffff0000, v186
	v_and_b32_e32 v28, 0xffff0000, v175
	v_mov_b32_e32 v132, v149
	v_mov_b32_e32 v60, v102
	v_mov_b32_e32 v61, v14
	v_pk_mul_f32 v[28:29], v[132:133], v[28:29]
	v_pk_add_f32 v[60:61], v[62:63], v[60:61]
	v_mov_b32_e32 v14, v103
	v_pk_add_f32 v[14:15], v[60:61], v[14:15]
	v_mov_b32_e32 v60, v2
	v_mov_b32_e32 v61, v28
	v_pk_add_f32 v[14:15], v[14:15], v[60:61]
	v_mov_b32_e32 v28, v3
	ds_read_b128 v[60:63], v124 offset:39296
	ds_read_b128 v[76:79], v124 offset:39312
	v_lshlrev_b32_e32 v2, 16, v170
	v_and_b32_e32 v3, 0xffff0000, v170
	v_pk_add_f32 v[14:15], v[14:15], v[28:29]
	v_pk_fma_f32 v[2:3], v[48:49], v[2:3], v[44:45]
	v_lshlrev_b32_e32 v28, 16, v4
	v_and_b32_e32 v29, 0xffff0000, v4
	v_pk_fma_f32 v[2:3], v[68:69], v[28:29], v[2:3]
	v_lshlrev_b32_e32 v28, 16, v181
	v_and_b32_e32 v29, 0xffff0000, v181
	v_pk_fma_f32 v[2:3], v[80:81], v[28:29], v[2:3]
	v_lshlrev_b32_e32 v28, 16, v193
	v_and_b32_e32 v29, 0xffff0000, v193
	s_waitcnt lgkmcnt(0)
; #define LAS __attribute__((address_space(3)))
; __device__ __forceinline__ unsigned cvt_pk_bf16(float lo, float hi) { unsigned r; asm volatile("v_cvt_pk_bf16_f32 %0, %1, %2" : "=v"(r) : "v"(lo), "v"(hi)); return r; }
; __device__ __forceinline__ float bf_lo(unsigned w) { return __uint_as_float(w << 16); }
; __device__ __forceinline__ float bf_hi(unsigned w) { return __uint_as_float(w & 0xffff0000u); }
; template <int PASS>
; __device__ __forceinline__ void lru_item(Frame& F, const LAS bf16* lw, const LAS float* prm, const LAS float* cwl, LAS float* xs, LAS unsigned char* pf, int head, int item, int nitem) {
;     ...
; #pragma unroll
;     for (int k = 0; k < 4; ++k)
; #pragma unroll
;         for (int ks = 0; ks < 4; ++ks) {
;             const u32x4 w = vw[k][ks]; const int ch = 16 * ks + 8 * hh;
;             const f32x4 c0 = *(const LAS f32x4*)(cwl + k * 64 + ch), c1 = *(const LAS f32x4*)(cwl + k * 64 + ch + 4);
;             xa[ks][0] += c0[0] * bf_lo(w.x); xa[ks][1] += c0[1] * bf_hi(w.x); xa[ks][2] += c0[2] * bf_lo(w.y); xa[ks][3] += c0[3] * bf_hi(w.y);
;             xa[ks][4] += c1[0] * bf_lo(w.z); xa[ks][5] += c1[1] * bf_hi(w.z); xa[ks][6] += c1[2] * bf_lo(w.w); xa[ks][7] += c1[3] * bf_hi(w.w);
;         }
;     bf16x8 af[4];
; #pragma unroll
;     for (int ks = 0; ks < 4; ++ks) {
;         u32x4 w; w.x = cvt_pk_bf16(xa[ks][0], xa[ks][1]); w.y = cvt_pk_bf16(xa[ks][2], xa[ks][3]); w.z = cvt_pk_bf16(xa[ks][4], xa[ks][5]); w.w = cvt_pk_bf16(xa[ks][6], xa[ks][7]);
;         af[ks] = __builtin_bit_cast(bf16x8, w);
;         *(LAS f32x4*)(xs + t * 68 + 16 * ks + 8 * hh) = (f32x4){xa[ks][0], xa[ks][1], xa[ks][2], xa[ks][3]};
;         *(LAS f32x4*)(xs + t * 68 + 16 * ks + 8 * hh + 4) = (f32x4){xa[ks][4], xa[ks][5], xa[ks][6], xa[ks][7]};
;     }
;     ...
;                 const LAS bf16* wb = lw + ((d * 2 + gt) * 64 + t + 32 * ct) * LRU_WROW + 8 * hh;
; #pragma unroll
;                 for (int ks = 0; ks < 4; ++ks) a = __builtin_amdgcn_mfma_f32_32x32x16_bf16(af[ks], *(const LAS bf16x8*)(wb + 16 * ks), a, 0, 0, 0);
	v_pk_fma_f32 v[2:3], v[60:61], v[28:29], v[2:3]
	v_lshlrev_b32_e32 v28, 16, v169
	v_and_b32_e32 v29, 0xffff0000, v169
	v_pk_fma_f32 v[28:29], v[50:51], v[28:29], v[46:47]
	v_lshlrev_b32_e32 v4, 16, v5
	v_and_b32_e32 v5, 0xffff0000, v5
	v_pk_fma_f32 v[4:5], v[70:71], v[4:5], v[28:29]
	v_lshlrev_b32_e32 v28, 16, v180
	v_and_b32_e32 v29, 0xffff0000, v180
	v_pk_fma_f32 v[4:5], v[82:83], v[28:29], v[4:5]
	v_lshlrev_b32_e32 v28, 16, v192
	v_and_b32_e32 v29, 0xffff0000, v192
	v_pk_fma_f32 v[4:5], v[62:63], v[28:29], v[4:5]
	v_lshlrev_b32_e32 v28, 16, v179
	v_lshlrev_b32_e32 v29, 16, v191
	v_mov_b32_e32 v44, v72
	v_mov_b32_e32 v45, v76
	v_pk_mul_f32 v[28:29], v[44:45], v[28:29]
	v_and_b32_e32 v45, 0xffff0000, v191
	v_and_b32_e32 v44, 0xffff0000, v179
	v_mov_b32_e32 v76, v73
	v_mov_b32_e32 v46, v98
	v_mov_b32_e32 v47, v100
	v_pk_mul_f32 v[44:45], v[76:77], v[44:45]
	v_pk_add_f32 v[24:25], v[24:25], v[46:47]
	v_mov_b32_e32 v100, v99
	v_pk_add_f32 v[24:25], v[24:25], v[100:101]
	v_mov_b32_e32 v46, v28
	v_mov_b32_e32 v47, v44
	v_pk_add_f32 v[24:25], v[24:25], v[46:47]
	v_mov_b32_e32 v44, v29
	v_pk_add_f32 v[24:25], v[24:25], v[44:45]
	v_lshlrev_b32_e32 v28, 16, v123
	v_lshlrev_b32_e32 v29, 16, v190
	v_mov_b32_e32 v44, v74
	v_mov_b32_e32 v45, v78
	v_pk_mul_f32 v[28:29], v[44:45], v[28:29]
	v_and_b32_e32 v45, 0xffff0000, v190
	v_and_b32_e32 v44, 0xffff0000, v123
	v_mov_b32_e32 v78, v75
	v_mov_b32_e32 v46, v94
	v_mov_b32_e32 v47, v96
	v_pk_mul_f32 v[44:45], v[78:79], v[44:45]
	v_pk_add_f32 v[26:27], v[26:27], v[46:47]
	v_mov_b32_e32 v96, v95
	v_pk_add_f32 v[26:27], v[26:27], v[96:97]
	v_mov_b32_e32 v46, v28
	v_mov_b32_e32 v47, v44
	v_pk_add_f32 v[26:27], v[26:27], v[46:47]
	v_mov_b32_e32 v44, v29
	v_pk_add_f32 v[26:27], v[26:27], v[44:45]
	ds_read_b128 v[44:47], v124 offset:39360
	ds_read_b128 v[48:51], v124 offset:39376
	v_lshlrev_b32_e32 v28, 16, v120
	v_and_b32_e32 v29, 0xffff0000, v120
	v_pk_fma_f32 v[16:17], v[20:21], v[28:29], v[16:17]
	v_lshlrev_b32_e32 v20, 16, v0
	v_and_b32_e32 v21, 0xffff0000, v0
	v_pk_fma_f32 v[16:17], v[40:41], v[20:21], v[16:17]
	v_lshlrev_b32_e32 v20, 16, v121
	v_and_b32_e32 v21, 0xffff0000, v121
	v_pk_fma_f32 v[16:17], v[56:57], v[20:21], v[16:17]
	v_lshlrev_b32_e32 v20, 16, v122
	v_and_b32_e32 v21, 0xffff0000, v122
	s_waitcnt lgkmcnt(0)
	v_pk_fma_f32 v[16:17], v[44:45], v[20:21], v[16:17]
	v_lshlrev_b32_e32 v20, 16, v117
	v_and_b32_e32 v21, 0xffff0000, v117
	v_pk_fma_f32 v[18:19], v[22:23], v[20:21], v[18:19]
	v_lshlrev_b32_e32 v0, 16, v1
	v_and_b32_e32 v1, 0xffff0000, v1
	v_pk_fma_f32 v[0:1], v[42:43], v[0:1], v[18:19]
	v_lshlrev_b32_e32 v18, 16, v118
	v_and_b32_e32 v19, 0xffff0000, v118
	v_pk_fma_f32 v[0:1], v[58:59], v[18:19], v[0:1]
	v_lshlrev_b32_e32 v18, 16, v119
	v_and_b32_e32 v19, 0xffff0000, v119
	v_pk_fma_f32 v[18:19], v[46:47], v[18:19], v[0:1]
	v_lshlrev_b32_e32 v0, 16, v115
	v_lshlrev_b32_e32 v1, 16, v116
	v_mov_b32_e32 v20, v30
	v_mov_b32_e32 v21, v48
	v_pk_mul_f32 v[0:1], v[20:21], v[0:1]
	v_and_b32_e32 v21, 0xffff0000, v116
	v_and_b32_e32 v20, 0xffff0000, v115
	v_mov_b32_e32 v48, v31
	v_mov_b32_e32 v22, v90
	v_mov_b32_e32 v23, v92
	v_pk_mul_f32 v[20:21], v[48:49], v[20:21]
	v_pk_add_f32 v[8:9], v[8:9], v[22:23]
	v_mov_b32_e32 v92, v91
	v_pk_add_f32 v[8:9], v[8:9], v[92:93]
	v_mov_b32_e32 v22, v0
	v_mov_b32_e32 v23, v20
	v_pk_add_f32 v[8:9], v[8:9], v[22:23]
	v_mov_b32_e32 v20, v1
	v_pk_add_f32 v[8:9], v[8:9], v[20:21]
	v_lshlrev_b32_e32 v0, 16, v113
	v_lshlrev_b32_e32 v1, 16, v114
	v_mov_b32_e32 v20, v32
	v_mov_b32_e32 v21, v50
	v_mov_b32_e32 v22, v6
	v_mov_b32_e32 v23, v34
	v_pk_mul_f32 v[0:1], v[20:21], v[0:1]
	v_and_b32_e32 v21, 0xffff0000, v114
	v_and_b32_e32 v20, 0xffff0000, v113
	v_mov_b32_e32 v50, v33
	v_pk_add_f32 v[10:11], v[10:11], v[22:23]
	v_mov_b32_e32 v34, v7
	v_pk_mul_f32 v[20:21], v[50:51], v[20:21]
	v_pk_add_f32 v[6:7], v[10:11], v[34:35]
	v_mov_b32_e32 v10, v0
	v_mov_b32_e32 v0, s44
	v_mov_b32_e32 v11, v20
	v_mad_u32_u24 v28, v110, s55, v0
	v_pk_add_f32 v[6:7], v[6:7], v[10:11]
	v_mov_b32_e32 v20, v1
	v_add_u32_e32 v0, v28, v88
	v_pk_add_f32 v[10:11], v[6:7], v[20:21]
	v_cvt_pk_bf16_f32 v32, v36, v37
	v_cvt_pk_bf16_f32 v33, v38, v39
	v_cvt_pk_bf16_f32 v34, v52, v53
	v_cvt_pk_bf16_f32 v35, v54, v55
	ds_write_b128 v0, v[36:39] offset:40960
	ds_write_b128 v0, v[52:55] offset:40976
	v_cvt_pk_bf16_f32 v36, v64, v65
	v_cvt_pk_bf16_f32 v37, v66, v67
	v_cvt_pk_bf16_f32 v38, v12, v13
	v_cvt_pk_bf16_f32 v39, v14, v15
	ds_write_b128 v0, v[64:67] offset:41024
	ds_write_b128 v0, v[12:15] offset:41040
	v_cvt_pk_bf16_f32 v40, v2, v3
	v_cvt_pk_bf16_f32 v41, v4, v5
	v_cvt_pk_bf16_f32 v42, v24, v25
	v_cvt_pk_bf16_f32 v43, v26, v27
	ds_write_b128 v0, v[2:5] offset:41088
	ds_write_b128 v0, v[24:27] offset:41104
	v_cvt_pk_bf16_f32 v44, v16, v17
	v_cvt_pk_bf16_f32 v45, v18, v19
	v_cvt_pk_bf16_f32 v46, v8, v9
	v_cvt_pk_bf16_f32 v47, v10, v11
	ds_write_b128 v0, v[16:19] offset:41152
	ds_write_b128 v0, v[8:11] offset:41168
	s_waitcnt lgkmcnt(0)
	v_lshl_add_u32 v84, v112, 4, 0
	v_mad_u32_u24 v70, v110, s69, v84
	v_mov_b32_e32 v226, v70
	ds_read_b128 v[194:197], v226
	ds_read_b128 v[198:201], v226 offset:32
	ds_read_b128 v[202:205], v226 offset:96
	ds_read_b128 v[206:209], v226 offset:64
	ds_read_b128 v[210:213], v226 offset:9216
	ds_read_b128 v[214:217], v226 offset:9248
	ds_read_b128 v[218:221], v226 offset:9280
	ds_read_b128 v[222:225], v226 offset:9312
	s_waitcnt lgkmcnt(0)
; #define LAS __attribute__((address_space(3)))
; template <int PASS>
; __device__ __forceinline__ void lru_item(Frame& F, const LAS bf16* lw, const LAS float* prm, const LAS float* cwl, LAS float* xs, LAS unsigned char* pf, int head, int item, int nitem) {
;     ...
;             f32x16 acc[2];
; #pragma unroll
;             for (int gt = 0; gt < 2; ++gt) {
;                 f32x16 a; for (int i = 0; i < 16; ++i) a[i] = 0.f;
;                 const LAS bf16* wb = lw + ((d * 2 + gt) * 64 + t + 32 * ct) * LRU_WROW + 8 * hh;
; #pragma unroll
;                 for (int ks = 0; ks < 4; ++ks) a = __builtin_amdgcn_mfma_f32_32x32x16_bf16(af[ks], *(const LAS bf16x8*)(wb + 16 * ks), a, 0, 0, 0);
;                 acc[gt] = a;
;             }
;             const int chl = t + 32 * ct, ch = head * 64 + chl;
;             float av[16], bv[16];
;             {
;                 const float br = prm[(d * 3 + 0) * 64 + chl], bi = prm[(d * 3 + 1) * 64 + chl], c8 = prm[(d * 3 + 2) * 64 + chl];
; #pragma unroll
;                 for (int rg = 0; rg < 16; ++rg) {
;                     const float rr = __builtin_amdgcn_rcpf(1.f + __builtin_amdgcn_exp2f(acc[0][rg] + br)), ei = 1.f + __builtin_amdgcn_exp2f(acc[1][rg] + bi);
;                     const float a = __builtin_amdgcn_exp2f(c8 * rr), om = fmaxf(fmaf(-a, a, 1.f), 1e-30f);
;                     av[rg] = a; bv[rg] = (om * __builtin_amdgcn_rsqf(om * ei * ei)) * xd[ct][rg];
;                 }
	v_mfma_f32_32x32x16_bf16 v[0:15], v[32:35], v[194:197], 0
	v_mul_i32_i24_e32 v24, 0xfffffef4, v110
	v_mul_lo_u32 v25, v112, s61
	v_add3_u32 v74, v28, v24, v25
	v_add_u32_e32 v24, 0xa800, v74
	v_add_u32_e32 v48, 0xb000, v74
	v_add_u32_e32 v54, 0xb800, v74
	v_mfma_f32_32x32x16_bf16 v[0:15], v[36:39], v[198:201], v[0:15]
	v_add_u32_e32 v71, 0xba00, v74
	s_mul_hi_i32 s8, s4, 0x7e07e07f
	s_lshr_b32 s9, s8, 31
	s_ashr_i32 s8, s8, 5
	s_add_i32 s8, s8, s9
	s_mul_i32 s9, s8, 0x41
	s_waitcnt lgkmcnt(0)
	v_mfma_f32_32x32x16_bf16 v[0:15], v[40:43], v[206:209], v[0:15]
	v_add_u32_e32 v16, 0xa000, v74
	ds_read2_b32 v[58:59], v16 offset1:32
	ds_read2_b32 v[64:65], v16 offset0:68 offset1:100
	ds_read2_b32 v[68:69], v16 offset0:136 offset1:168
	ds_read2_b32 v[72:73], v16 offset0:204 offset1:236
	ds_read2_b32 v[50:51], v24 offset0:32 offset1:64
	ds_read2_b32 v[60:61], v24 offset0:100 offset1:132
	ds_read2_b32 v[66:67], v24 offset0:168 offset1:200
	s_sub_i32 s4, s4, s9
	s_lshl_b32 s9, s4, 3
	s_add_i32 s9, s9, 8
	s_cmp_lt_i32 s4, 64
	v_mfma_f32_32x32x16_bf16 v[0:15], v[44:47], v[202:205], v[0:15]
	v_add_u32_e32 v20, 0xaa00, v74
	ds_read2_b32 v[78:79], v20 offset0:108 offset1:140
	ds_read2_b32 v[52:53], v48 offset0:64 offset1:96
	ds_read2_b32 v[56:57], v48 offset0:132 offset1:164
	ds_read2_b32 v[62:63], v48 offset0:200 offset1:232
	v_add_u32_e32 v48, 0xb400, v74
	ds_read2_b32 v[76:77], v48 offset0:12 offset1:44
	ds_read2_b32 v[48:49], v54 offset0:96 offset1:128
	ds_read2_b32 v[54:55], v54 offset0:164 offset1:196
	s_waitcnt lgkmcnt(0)
	v_mfma_f32_32x32x16_bf16 v[16:31], v[32:35], v[210:213], 0
	v_add_u32_e32 v74, 0xbc00, v74
	ds_read2_b32 v[74:75], v74 offset0:44 offset1:76
	s_cselect_b32 s4, s9, 0
	s_or_b32 s4, s4, s17
	s_mulk_i32 s8, 0x410
	s_add_i32 s8, s4, s8
	s_ashr_i32 s9, s8, 31
	v_mfma_f32_32x32x16_bf16 v[16:31], v[36:39], v[214:217], v[16:31]
	v_lshl_add_u32 v83, v110, 2, 0
	ds_read2st64_b32 v[80:81], v83 offset0:144 offset1:145
	ds_read_b32 v85, v83 offset:37376
	ds_read2_b32 v[70:71], v71 offset0:104 offset1:136
	v_lshlrev_b32_e32 v82, 2, v111
	v_xor_b32_e32 v82, 0x80, v82
	s_waitcnt lgkmcnt(0)
	v_add_f32_e32 v4, v4, v80
	v_mfma_f32_32x32x16_bf16 v[16:31], v[40:43], v[218:221], v[16:31]
	v_exp_f32_e32 v4, v4
	v_add_f32_e32 v5, v5, v80
	v_exp_f32_e32 v5, v5
	v_add_f32_e32 v6, v6, v80
	v_add_f32_e32 v4, 1.0, v4
	v_rcp_f32_e32 v4, v4
	v_exp_f32_e32 v6, v6
	v_mfma_f32_32x32x16_bf16 v[16:31], v[44:47], v[222:225], v[16:31]
	ds_read_b128 v[194:197], v226 offset:4608
	ds_read_b128 v[198:201], v226 offset:4640
	ds_read_b128 v[202:205], v226 offset:4672
	ds_read_b128 v[206:209], v226 offset:4704
	ds_read_b128 v[210:213], v226 offset:13824
	ds_read_b128 v[214:217], v226 offset:13856
	ds_read_b128 v[218:221], v226 offset:13888
	ds_read_b128 v[222:225], v226 offset:13920
	v_add_f32_e32 v5, 1.0, v5
	v_mul_f32_e32 v4, v85, v4
	v_exp_f32_e32 v4, v4
	v_rcp_f32_e32 v5, v5
	v_add_f32_e32 v6, 1.0, v6
	v_rcp_f32_e32 v6, v6
	v_fma_f32 v86, -v4, v4, 1.0
	s_nop 4
	v_add_f32_e32 v20, v20, v81
	v_exp_f32_e32 v20, v20
	v_max_f32_e32 v86, 0xda24260, v86
	v_add_f32_e32 v7, v7, v80
	v_mul_f32_e32 v5, v85, v5
	v_add_f32_e32 v20, 1.0, v20
	v_mul_f32_e32 v87, v20, v86
	v_mul_f32_e32 v20, v20, v87
	v_exp_f32_e32 v7, v7
	v_rsq_f32_e32 v20, v20
	v_add_f32_e32 v21, v21, v81
	v_exp_f32_e32 v5, v5
	v_exp_f32_e32 v21, v21
	v_add_f32_e32 v8, v8, v80
	v_mul_f32_e32 v6, v85, v6
	v_exp_f32_e32 v8, v8
	v_add_f32_e32 v22, v22, v81
	v_exp_f32_e32 v6, v6
	v_add_f32_e32 v7, 1.0, v7
	v_mul_f32_e32 v20, v86, v20
	v_fma_f32 v86, -v5, v5, 1.0
	v_exp_f32_e32 v22, v22
	v_rcp_f32_e32 v7, v7
	v_add_f32_e32 v21, 1.0, v21
	v_max_f32_e32 v86, 0xda24260, v86
	v_mul_f32_e32 v87, v21, v86
	v_add_f32_e32 v8, 1.0, v8
	v_mul_f32_e32 v21, v21, v87
	v_fma_f32 v87, -v6, v6, 1.0
	v_rcp_f32_e32 v8, v8
	v_add_f32_e32 v9, v9, v80
	v_add_f32_e32 v22, 1.0, v22
	v_max_f32_e32 v87, 0xda24260, v87
	v_mul_f32_e32 v7, v85, v7
	v_exp_f32_e32 v9, v9
	v_rsq_f32_e32 v21, v21
	v_mul_f32_e32 v88, v22, v87
	v_add_f32_e32 v23, v23, v81
	v_exp_f32_e32 v7, v7
	v_mul_f32_e32 v22, v22, v88
	v_exp_f32_e32 v23, v23
	v_rsq_f32_e32 v22, v22
	v_mul_f32_e32 v8, v85, v8
	v_add_f32_e32 v24, v24, v81
	v_exp_f32_e32 v8, v8
	v_add_f32_e32 v9, 1.0, v9
	v_mul_f32_e32 v21, v86, v21
	v_fma_f32 v86, -v7, v7, 1.0
	v_exp_f32_e32 v24, v24
	v_rcp_f32_e32 v9, v9
	v_add_f32_e32 v23, 1.0, v23
	v_max_f32_e32 v86, 0xda24260, v86
	v_mul_f32_e32 v22, v87, v22
	v_mul_f32_e32 v87, v23, v86
	v_add_f32_e32 v10, v10, v80
	v_mul_f32_e32 v23, v23, v87
	v_fma_f32 v87, -v8, v8, 1.0
	v_exp_f32_e32 v10, v10
	v_add_f32_e32 v24, 1.0, v24
	v_max_f32_e32 v87, 0xda24260, v87
	v_mul_f32_e32 v9, v85, v9
	v_rsq_f32_e32 v23, v23
	v_mul_f32_e32 v88, v24, v87
	v_add_f32_e32 v25, v25, v81
	v_exp_f32_e32 v9, v9
	v_add_f32_e32 v11, v11, v80
	v_mul_f32_e32 v24, v24, v88
	v_exp_f32_e32 v25, v25
	v_exp_f32_e32 v11, v11
	v_rsq_f32_e32 v24, v24
	v_add_f32_e32 v10, 1.0, v10
	v_rcp_f32_e32 v10, v10
	v_mul_f32_e32 v23, v86, v23
	v_fma_f32 v86, -v9, v9, 1.0
	v_add_f32_e32 v25, 1.0, v25
	v_max_f32_e32 v86, 0xda24260, v86
	v_add_f32_e32 v11, 1.0, v11
	v_mul_f32_e32 v24, v87, v24
	v_mul_f32_e32 v87, v25, v86
	v_rcp_f32_e32 v11, v11
	v_add_f32_e32 v12, v12, v80
	v_mul_f32_e32 v25, v25, v87
	v_mul_f32_e32 v10, v85, v10
	v_exp_f32_e32 v12, v12
	v_rsq_f32_e32 v25, v25
	v_add_f32_e32 v26, v26, v81
	v_exp_f32_e32 v10, v10
	v_exp_f32_e32 v26, v26
	v_mul_f32_e32 v11, v85, v11
	v_add_f32_e32 v27, v27, v81
	v_exp_f32_e32 v11, v11
	v_add_f32_e32 v12, 1.0, v12
	v_mul_f32_e32 v25, v86, v25
	v_fma_f32 v86, -v10, v10, 1.0
	v_exp_f32_e32 v27, v27
	v_rcp_f32_e32 v12, v12
	v_add_f32_e32 v26, 1.0, v26
; template <int PASS>
; __device__ __forceinline__ void lru_item(Frame& F, const LAS bf16* lw, const LAS float* prm, const LAS float* cwl, LAS float* xs, LAS unsigned char* pf, int head, int item, int nitem) {
;     ...
;                 const float br = prm[(d * 3 + 0) * 64 + chl], bi = prm[(d * 3 + 1) * 64 + chl], c8 = prm[(d * 3 + 2) * 64 + chl];
; #pragma unroll
;                 for (int rg = 0; rg < 16; ++rg) {
;                     const float rr = __builtin_amdgcn_rcpf(1.f + __builtin_amdgcn_exp2f(acc[0][rg] + br)), ei = 1.f + __builtin_amdgcn_exp2f(acc[1][rg] + bi);
;                     const float a = __builtin_amdgcn_exp2f(c8 * rr), om = fmaxf(fmaf(-a, a, 1.f), 1e-30f);
;                     av[rg] = a; bv[rg] = (om * __builtin_amdgcn_rsqf(om * ei * ei)) * xd[ct][rg];
;                 }
;             }
;             float hl[16], cp[16], sA[4], sB[4];
; #pragma unroll
;             for (int q4 = 0; q4 < 4; ++q4) {
;                 if (d == 0) {
;                     hl[4 * q4] = bv[4 * q4]; cp[4 * q4] = av[4 * q4];
; #pragma unroll
;                     for (int i = 1; i < 4; ++i) { hl[4 * q4 + i] = av[4 * q4 + i] * hl[4 * q4 + i - 1] + bv[4 * q4 + i]; cp[4 * q4 + i] = av[4 * q4 + i] * cp[4 * q4 + i - 1]; }
;                     sA[q4] = cp[4 * q4 + 3]; sB[q4] = hl[4 * q4 + 3];
;                 } else {
;                     hl[4 * q4 + 3] = bv[4 * q4 + 3]; cp[4 * q4 + 3] = av[4 * q4 + 3];
; #pragma unroll
;                     for (int i = 2; i >= 0; --i) { hl[4 * q4 + i] = av[4 * q4 + i] * hl[4 * q4 + i + 1] + bv[4 * q4 + i]; cp[4 * q4 + i] = av[4 * q4 + i] * cp[4 * q4 + i + 1]; }
;                     sA[q4] = cp[4 * q4]; sB[q4] = hl[4 * q4];
;                 }
;             }
;             float Ae[4], Be[4], Ao[4], Bo[4];
; #pragma unroll
;             for (int q4 = 0; q4 < 4; ++q4) {
;                 const float oA = shx(sA[q4], 32, lane), oB = shx(sB[q4], 32, lane);
;                 Ae[q4] = hh ? oA : sA[q4]; Be[q4] = hh ? oB : sB[q4]; Ao[q4] = hh ? sA[q4] : oA; Bo[q4] = hh ? sB[q4] : oB;
;             }
;             if (PASS == 1) {
;                 float c = 0.f, P = 1.f;
;                 if (d == 0) {
; #pragma unroll
;                     for (int q4 = 0; q4 < 4; ++q4) { c = Ae[q4] * c + Be[q4]; c = Ao[q4] * c + Bo[q4]; P *= Ae[q4] * Ao[q4]; } }
;                 else {
; #pragma unroll
	v_max_f32_e32 v86, 0xda24260, v86
	v_mul_f32_e32 v87, v26, v86
	v_add_f32_e32 v13, v13, v80
	v_mul_f32_e32 v26, v26, v87
	v_fma_f32 v87, -v11, v11, 1.0
	v_exp_f32_e32 v13, v13
	v_add_f32_e32 v27, 1.0, v27
	v_max_f32_e32 v87, 0xda24260, v87
	v_mul_f32_e32 v12, v85, v12
	v_rsq_f32_e32 v26, v26
	v_mul_f32_e32 v88, v27, v87
	v_add_f32_e32 v28, v28, v81
	v_exp_f32_e32 v12, v12
	v_add_f32_e32 v14, v14, v80
	v_mul_f32_e32 v27, v27, v88
	v_exp_f32_e32 v28, v28
	v_exp_f32_e32 v14, v14
	v_rsq_f32_e32 v27, v27
	v_add_f32_e32 v13, 1.0, v13
	v_rcp_f32_e32 v13, v13
	v_add_f32_e32 v15, v15, v80
	v_mul_f32_e32 v26, v86, v26
	v_fma_f32 v86, -v12, v12, 1.0
	v_exp_f32_e32 v15, v15
	v_add_f32_e32 v28, 1.0, v28
	v_max_f32_e32 v86, 0xda24260, v86
	v_add_f32_e32 v14, 1.0, v14
	v_mul_f32_e32 v27, v87, v27
	v_mul_f32_e32 v87, v28, v86
	v_rcp_f32_e32 v14, v14
	v_add_f32_e32 v3, v3, v80
	v_mul_f32_e32 v28, v28, v87
	v_mul_f32_e32 v13, v85, v13
	v_exp_f32_e32 v3, v3
	v_rsq_f32_e32 v28, v28
	v_add_f32_e32 v29, v29, v81
	v_exp_f32_e32 v13, v13
	v_add_f32_e32 v15, 1.0, v15
	v_exp_f32_e32 v29, v29
	v_rcp_f32_e32 v15, v15
	v_add_f32_e32 v2, v2, v80
	v_mul_f32_e32 v14, v85, v14
	v_exp_f32_e32 v2, v2
	v_add_f32_e32 v0, v0, v80
	v_add_f32_e32 v30, v30, v81
	v_exp_f32_e32 v14, v14
	v_add_f32_e32 v3, 1.0, v3
	v_exp_f32_e32 v0, v0
	v_mul_f32_e32 v28, v86, v28
	v_fma_f32 v86, -v13, v13, 1.0
	v_exp_f32_e32 v30, v30
	v_rcp_f32_e32 v3, v3
	v_add_f32_e32 v1, v1, v80
	v_add_f32_e32 v29, 1.0, v29
	v_max_f32_e32 v86, 0xda24260, v86
	v_mul_f32_e32 v15, v85, v15
	v_exp_f32_e32 v1, v1
	v_mul_f32_e32 v87, v29, v86
	v_add_f32_e32 v31, v31, v81
	v_exp_f32_e32 v15, v15
	v_add_f32_e32 v2, 1.0, v2
	v_mul_f32_e32 v29, v29, v87
	v_fma_f32 v87, -v14, v14, 1.0
	v_exp_f32_e32 v31, v31
	v_rcp_f32_e32 v2, v2
	v_add_f32_e32 v0, 1.0, v0
	v_add_f32_e32 v30, 1.0, v30
	v_max_f32_e32 v87, 0xda24260, v87
	v_mul_f32_e32 v3, v85, v3
	v_rcp_f32_e32 v0, v0
	v_rsq_f32_e32 v29, v29
	v_mul_f32_e32 v88, v30, v87
	v_exp_f32_e32 v3, v3
	v_add_f32_e32 v19, v19, v81
	v_add_f32_e32 v1, 1.0, v1
	v_mul_f32_e32 v30, v30, v88
	v_fma_f32 v88, -v15, v15, 1.0
	v_exp_f32_e32 v19, v19
	v_rcp_f32_e32 v1, v1
	v_rsq_f32_e32 v30, v30
	v_add_f32_e32 v31, 1.0, v31
	v_max_f32_e32 v88, 0xda24260, v88
	v_mul_f32_e32 v2, v85, v2
	v_mul_f32_e32 v90, v31, v88
	v_exp_f32_e32 v2, v2
	v_add_f32_e32 v18, v18, v81
	v_mul_f32_e32 v0, v85, v0
	v_mul_f32_e32 v31, v31, v90
	v_mul_f32_e32 v29, v86, v29
	v_fma_f32 v86, -v3, v3, 1.0
	v_exp_f32_e32 v18, v18
	v_exp_f32_e32 v0, v0
	v_add_f32_e32 v16, v16, v81
	v_rsq_f32_e32 v31, v31
	v_max_f32_e32 v86, 0xda24260, v86
	v_add_f32_e32 v19, 1.0, v19
	v_mul_f32_e32 v1, v85, v1
	v_exp_f32_e32 v16, v16
	v_mul_f32_e32 v30, v87, v30
	v_mul_f32_e32 v87, v19, v86
	v_exp_f32_e32 v1, v1
	v_add_f32_e32 v17, v17, v81
	v_mul_f32_e32 v19, v19, v87
	v_fma_f32 v87, -v2, v2, 1.0
	v_exp_f32_e32 v17, v17
	v_max_f32_e32 v87, 0xda24260, v87
	v_add_f32_e32 v18, 1.0, v18
	v_fma_f32 v81, -v0, v0, 1.0
	v_mul_f32_e32 v31, v88, v31
	v_mul_f32_e32 v88, v18, v87
	v_max_f32_e32 v81, 0xda24260, v81
	v_add_f32_e32 v16, 1.0, v16
	v_mul_f32_e32 v18, v18, v88
	v_fma_f32 v88, -v1, v1, 1.0
	v_mul_f32_e32 v85, v16, v81
	v_max_f32_e32 v80, 0xda24260, v88
	v_add_f32_e32 v17, 1.0, v17
	v_mul_f32_e32 v16, v16, v85
	v_mul_f32_e32 v88, v17, v80
	v_rsq_f32_e32 v16, v16
	v_mul_f32_e32 v17, v17, v88
	v_rsq_f32_e32 v17, v17
	v_rsq_f32_e32 v18, v18
	v_mul_f32_e32 v16, v81, v16
	v_mul_f32_e32 v16, v58, v16
	v_mul_f32_e32 v17, v80, v17
	v_mul_f32_e32 v16, v1, v16
	v_fmac_f32_e32 v16, v64, v17
	v_mul_f32_e32 v18, v87, v18
	v_mul_f32_e32 v0, v0, v1
	v_mul_f32_e32 v1, v2, v16
	v_mul_f32_e32 v20, v50, v20
	v_fmac_f32_e32 v1, v68, v18
	v_mul_f32_e32 v0, v2, v0
	v_mul_f32_e32 v2, v3, v1
	v_mul_f32_e32 v3, v3, v0
	v_mul_f32_e32 v0, v5, v20
	v_fmac_f32_e32 v0, v60, v21
	v_mul_f32_e32 v0, v6, v0
	v_mul_f32_e32 v24, v52, v24
	v_fmac_f32_e32 v0, v66, v22
	v_mul_f32_e32 v1, v4, v5
	v_mul_f32_e32 v4, v7, v0
	v_mul_f32_e32 v0, v9, v24
	v_fmac_f32_e32 v0, v56, v25
	v_mul_f32_e32 v0, v10, v0
	v_mul_f32_e32 v28, v48, v28
	v_fmac_f32_e32 v0, v62, v26
	v_rsq_f32_e32 v19, v19
	v_mul_f32_e32 v1, v6, v1
	v_mul_f32_e32 v6, v11, v0
	v_mul_f32_e32 v0, v13, v28
	v_mul_f32_e32 v5, v7, v1
	v_mul_f32_e32 v1, v8, v9
	v_fmac_f32_e32 v0, v54, v29
	v_mul_f32_e32 v1, v10, v1
	v_mul_f32_e32 v0, v14, v0
	v_mul_f32_e32 v7, v11, v1
	v_mul_f32_e32 v1, v12, v13
	v_fmac_f32_e32 v0, v70, v30
	v_mul_f32_e32 v19, v86, v19
	v_mul_f32_e32 v1, v14, v1
	v_mul_f32_e32 v8, v15, v0
	v_fmac_f32_e32 v2, v72, v19
	v_fmac_f32_e32 v4, v78, v23
	v_fmac_f32_e32 v6, v76, v27
	v_fmac_f32_e32 v8, v74, v31
	v_mul_f32_e32 v9, v15, v1
	s_nop 1
	v_permlane32_swap_b32 v3, v16
	v_permlane32_swap_b32 v2, v15
	v_permlane32_swap_b32 v5, v14
	v_permlane32_swap_b32 v4, v13
	v_permlane32_swap_b32 v7, v12
	v_permlane32_swap_b32 v6, v11
	v_permlane32_swap_b32 v9, v10
	v_permlane32_swap_b32 v8, v1
	v_cmp_gt_u32_e32 vcc, 32, v111
	s_lshl_b64 s[10:11], s[8:9], 11
	v_lshl_or_b32 v88, v111, 1, s16
	s_and_saveexec_b64 s[12:13], vcc
	s_cbranch_execz .LBB0_704
	v_fmac_f32_e32 v2, 0, v3
	s_waitcnt lgkmcnt(0)
	v_fmac_f32_e32 v15, v2, v16
	v_fmac_f32_e32 v4, v5, v15
	v_fmac_f32_e32 v13, v4, v14
	v_mul_f32_e32 v0, v3, v16
	v_mul_f32_e32 v17, v5, v14
	v_fmac_f32_e32 v6, v7, v13
	s_lshl_b64 s[62:63], s[10:11], 2
	v_mul_f32_e32 v0, v0, v17
	v_mul_f32_e32 v17, v7, v12
	v_fmac_f32_e32 v11, v6, v12
	s_add_u32 s62, s19, s62
	v_mul_f32_e32 v0, v17, v0
	v_mul_f32_e32 v17, v9, v10
	v_fmac_f32_e32 v8, v9, v11
	s_addc_u32 s63, s30, s63
	v_mul_f32_e32 v0, v17, v0
	v_fmac_f32_e32 v1, v8, v10
	v_lshl_add_u64 v[2:3], v[88:89], 2, s[62:63]
	global_store_dwordx2 v[2:3], v[0:1], off
; #define LAS __attribute__((address_space(3)))
; template <int PASS>
; __device__ __forceinline__ void lru_item(Frame& F, const LAS bf16* lw, const LAS float* prm, const LAS float* cwl, LAS float* xs, LAS unsigned char* pf, int head, int item, int nitem) {
;     ...
;             f32x16 acc[2];
; #pragma unroll
;             for (int gt = 0; gt < 2; ++gt) {
;                 f32x16 a; for (int i = 0; i < 16; ++i) a[i] = 0.f;
;                 const LAS bf16* wb = lw + ((d * 2 + gt) * 64 + t + 32 * ct) * LRU_WROW + 8 * hh;
; #pragma unroll
;                 for (int ks = 0; ks < 4; ++ks) a = __builtin_amdgcn_mfma_f32_32x32x16_bf16(af[ks], *(const LAS bf16x8*)(wb + 16 * ks), a, 0, 0, 0);
;                 acc[gt] = a;
;             }
;             const int chl = t + 32 * ct, ch = head * 64 + chl;
;             float av[16], bv[16];
;             {
;                 const float br = prm[(d * 3 + 0) * 64 + chl], bi = prm[(d * 3 + 1) * 64 + chl], c8 = prm[(d * 3 + 2) * 64 + chl];
; #pragma unroll
;                 for (int rg = 0; rg < 16; ++rg) {
;                     const float rr = __builtin_amdgcn_rcpf(1.f + __builtin_amdgcn_exp2f(acc[0][rg] + br)), ei = 1.f + __builtin_amdgcn_exp2f(acc[1][rg] + bi);
;                     const float a = __builtin_amdgcn_exp2f(c8 * rr), om = fmaxf(fmaf(-a, a, 1.f), 1e-30f);
;                     av[rg] = a; bv[rg] = (om * __builtin_amdgcn_rsqf(om * ei * ei)) * xd[ct][rg];
;                 }
.LBB0_704:
	s_or_b64 exec, exec, s[12:13]
	v_mul_u32_u24_e32 v0, 0x90, v110
	v_add_u32_e32 v85, v84, v0
	s_waitcnt lgkmcnt(0)
	ds_read_b32 v84, v83 offset:37504
	v_add_u32_e32 v86, 0x80, v83
	s_waitcnt lgkmcnt(0)
	v_mfma_f32_32x32x16_bf16 v[16:31], v[32:35], v[194:197], 0
	s_waitcnt lgkmcnt(0)
	v_mfma_f32_32x32x16_bf16 v[16:31], v[36:39], v[198:201], v[16:31]
	v_mfma_f32_32x32x16_bf16 v[16:31], v[40:43], v[202:205], v[16:31]
	ds_read2st64_b32 v[80:81], v86 offset0:144 offset1:145
	s_waitcnt lgkmcnt(0)
	v_mfma_f32_32x32x16_bf16 v[16:31], v[44:47], v[206:209], v[16:31]
	v_mfma_f32_32x32x16_bf16 v[0:15], v[32:35], v[210:213], 0
	s_nop 10
	v_add_f32_e32 v20, v20, v80
	v_exp_f32_e32 v20, v20
	v_add_f32_e32 v21, v21, v80
	v_exp_f32_e32 v21, v21
	v_add_f32_e32 v22, v22, v80
	v_add_f32_e32 v20, 1.0, v20
	v_rcp_f32_e32 v20, v20
	v_mfma_f32_32x32x16_bf16 v[0:15], v[36:39], v[214:217], v[0:15]
	v_exp_f32_e32 v22, v22
	v_mul_f32_e32 v20, v84, v20
	v_exp_f32_e32 v20, v20
	v_add_f32_e32 v21, 1.0, v21
	v_rcp_f32_e32 v21, v21
	v_add_f32_e32 v22, 1.0, v22
	v_mfma_f32_32x32x16_bf16 v[0:15], v[40:43], v[218:221], v[0:15]
	v_fma_f32 v87, -v20, v20, 1.0
	v_max_f32_e32 v87, 0xda24260, v87
	v_rcp_f32_e32 v22, v22
	v_add_f32_e32 v23, v23, v80
	v_mul_f32_e32 v21, v84, v21
	v_exp_f32_e32 v23, v23
	v_exp_f32_e32 v21, v21
	s_waitcnt lgkmcnt(0)
	v_mfma_f32_32x32x16_bf16 v[0:15], v[44:47], v[222:225], v[0:15]
	ds_read_b128 v[194:197], v226 offset:18432
	ds_read_b128 v[198:201], v226 offset:18464
	ds_read_b128 v[202:205], v226 offset:18496
	ds_read_b128 v[206:209], v226 offset:18528
	ds_read_b128 v[210:213], v226 offset:27648
	ds_read_b128 v[214:217], v226 offset:27680
	ds_read_b128 v[218:221], v226 offset:27712
	ds_read_b128 v[222:225], v226 offset:27744
	v_add_f32_e32 v24, v24, v80
	v_mul_f32_e32 v22, v84, v22
	v_exp_f32_e32 v24, v24
	v_exp_f32_e32 v22, v22
	v_add_f32_e32 v23, 1.0, v23
	v_rcp_f32_e32 v23, v23
	v_add_f32_e32 v24, 1.0, v24
	s_nop 4
	v_add_f32_e32 v4, v4, v81
	v_exp_f32_e32 v4, v4
	v_add_f32_e32 v5, v5, v81
	v_exp_f32_e32 v5, v5
	v_add_f32_e32 v6, v6, v81
	v_add_f32_e32 v4, 1.0, v4
	v_mul_f32_e32 v90, v4, v87
	v_mul_f32_e32 v4, v4, v90
	v_rsq_f32_e32 v4, v4
	v_exp_f32_e32 v6, v6
	v_add_f32_e32 v5, 1.0, v5
	v_rcp_f32_e32 v24, v24
	v_mul_f32_e32 v4, v87, v4
	v_fma_f32 v87, -v21, v21, 1.0
	v_max_f32_e32 v87, 0xda24260, v87
	v_mul_f32_e32 v90, v5, v87
	v_mul_f32_e32 v5, v5, v90
	v_fma_f32 v90, -v22, v22, 1.0
	v_add_f32_e32 v25, v25, v80
	v_add_f32_e32 v6, 1.0, v6
	v_max_f32_e32 v90, 0xda24260, v90
	v_mul_f32_e32 v23, v84, v23
	v_exp_f32_e32 v25, v25
	v_rsq_f32_e32 v5, v5
	v_mul_f32_e32 v91, v6, v90
	v_add_f32_e32 v7, v7, v81
	v_exp_f32_e32 v23, v23
	v_mul_f32_e32 v6, v6, v91
	v_exp_f32_e32 v7, v7
	v_rsq_f32_e32 v6, v6
	v_mul_f32_e32 v24, v84, v24
	v_add_f32_e32 v8, v8, v81
	v_exp_f32_e32 v24, v24
	v_add_f32_e32 v25, 1.0, v25
	v_mul_f32_e32 v5, v87, v5
	v_fma_f32 v87, -v23, v23, 1.0
	v_exp_f32_e32 v8, v8
	v_rcp_f32_e32 v25, v25
	v_add_f32_e32 v7, 1.0, v7
	v_max_f32_e32 v87, 0xda24260, v87
	v_mul_f32_e32 v6, v90, v6
	v_mul_f32_e32 v90, v7, v87
	v_add_f32_e32 v26, v26, v80
	v_mul_f32_e32 v7, v7, v90
	v_fma_f32 v90, -v24, v24, 1.0
	v_exp_f32_e32 v26, v26
	v_add_f32_e32 v8, 1.0, v8
	v_max_f32_e32 v90, 0xda24260, v90
	v_mul_f32_e32 v25, v84, v25
	v_rsq_f32_e32 v7, v7
	v_mul_f32_e32 v91, v8, v90
	v_add_f32_e32 v9, v9, v81
	v_exp_f32_e32 v25, v25
	v_add_f32_e32 v27, v27, v80
	v_mul_f32_e32 v8, v8, v91
	v_exp_f32_e32 v9, v9
	v_exp_f32_e32 v27, v27
	v_rsq_f32_e32 v8, v8
	v_add_f32_e32 v26, 1.0, v26
	v_rcp_f32_e32 v26, v26
	v_mul_f32_e32 v7, v87, v7
	v_fma_f32 v87, -v25, v25, 1.0
	v_add_f32_e32 v9, 1.0, v9
	v_max_f32_e32 v87, 0xda24260, v87
	v_add_f32_e32 v27, 1.0, v27
	v_mul_f32_e32 v8, v90, v8
	v_mul_f32_e32 v90, v9, v87
	v_rcp_f32_e32 v27, v27
	v_add_f32_e32 v28, v28, v80
	v_mul_f32_e32 v9, v9, v90
	v_mul_f32_e32 v26, v84, v26
	v_exp_f32_e32 v28, v28
	v_rsq_f32_e32 v9, v9
	v_add_f32_e32 v10, v10, v81
	v_exp_f32_e32 v26, v26
	v_exp_f32_e32 v10, v10
	v_mul_f32_e32 v27, v84, v27
	v_add_f32_e32 v11, v11, v81
	v_exp_f32_e32 v27, v27
	v_add_f32_e32 v28, 1.0, v28
	v_mul_f32_e32 v9, v87, v9
	v_fma_f32 v87, -v26, v26, 1.0
	v_exp_f32_e32 v11, v11
	v_rcp_f32_e32 v28, v28
	v_add_f32_e32 v10, 1.0, v10
	v_max_f32_e32 v87, 0xda24260, v87
	v_mul_f32_e32 v90, v10, v87
	v_add_f32_e32 v29, v29, v80
	v_mul_f32_e32 v10, v10, v90
	v_fma_f32 v90, -v27, v27, 1.0
	v_exp_f32_e32 v29, v29
	v_add_f32_e32 v11, 1.0, v11
	v_max_f32_e32 v90, 0xda24260, v90
	v_mul_f32_e32 v28, v84, v28
	v_rsq_f32_e32 v10, v10
	v_mul_f32_e32 v91, v11, v90
	v_add_f32_e32 v12, v12, v81
	v_exp_f32_e32 v28, v28
	v_add_f32_e32 v30, v30, v80
	v_mul_f32_e32 v11, v11, v91
	v_exp_f32_e32 v12, v12
	v_exp_f32_e32 v30, v30
	v_rsq_f32_e32 v11, v11
	v_add_f32_e32 v29, 1.0, v29
	v_rcp_f32_e32 v29, v29
	v_add_f32_e32 v31, v31, v80
	v_mul_f32_e32 v10, v87, v10
	v_fma_f32 v87, -v28, v28, 1.0
	v_exp_f32_e32 v31, v31
	v_add_f32_e32 v12, 1.0, v12
	v_max_f32_e32 v87, 0xda24260, v87
	v_add_f32_e32 v30, 1.0, v30
	v_mul_f32_e32 v11, v90, v11
	v_mul_f32_e32 v90, v12, v87
	v_rcp_f32_e32 v30, v30
	v_add_f32_e32 v19, v19, v80
	v_mul_f32_e32 v12, v12, v90
	v_mul_f32_e32 v29, v84, v29
	v_exp_f32_e32 v19, v19
	v_rsq_f32_e32 v12, v12
	v_add_f32_e32 v13, v13, v81
	v_exp_f32_e32 v29, v29
	v_add_f32_e32 v31, 1.0, v31
	v_exp_f32_e32 v13, v13
	v_rcp_f32_e32 v31, v31
	v_add_f32_e32 v18, v18, v80
	v_mul_f32_e32 v30, v84, v30
	v_exp_f32_e32 v18, v18
	v_add_f32_e32 v16, v16, v80
	v_add_f32_e32 v14, v14, v81
	v_exp_f32_e32 v30, v30
	v_add_f32_e32 v19, 1.0, v19
	v_exp_f32_e32 v16, v16
	v_mul_f32_e32 v12, v87, v12
	v_fma_f32 v87, -v29, v29, 1.0
; template <int PASS>
; __device__ __forceinline__ void lru_item(Frame& F, const LAS bf16* lw, const LAS float* prm, const LAS float* cwl, LAS float* xs, LAS unsigned char* pf, int head, int item, int nitem) {
;     ...
;                 const float br = prm[(d * 3 + 0) * 64 + chl], bi = prm[(d * 3 + 1) * 64 + chl], c8 = prm[(d * 3 + 2) * 64 + chl];
; #pragma unroll
;                 for (int rg = 0; rg < 16; ++rg) {
;                     const float rr = __builtin_amdgcn_rcpf(1.f + __builtin_amdgcn_exp2f(acc[0][rg] + br)), ei = 1.f + __builtin_amdgcn_exp2f(acc[1][rg] + bi);
;                     const float a = __builtin_amdgcn_exp2f(c8 * rr), om = fmaxf(fmaf(-a, a, 1.f), 1e-30f);
;                     av[rg] = a; bv[rg] = (om * __builtin_amdgcn_rsqf(om * ei * ei)) * xd[ct][rg];
;                 }
;             }
;             float hl[16], cp[16], sA[4], sB[4];
; #pragma unroll
;             for (int q4 = 0; q4 < 4; ++q4) {
;                 if (d == 0) {
;                     hl[4 * q4] = bv[4 * q4]; cp[4 * q4] = av[4 * q4];
; #pragma unroll
;                     for (int i = 1; i < 4; ++i) { hl[4 * q4 + i] = av[4 * q4 + i] * hl[4 * q4 + i - 1] + bv[4 * q4 + i]; cp[4 * q4 + i] = av[4 * q4 + i] * cp[4 * q4 + i - 1]; }
;                     sA[q4] = cp[4 * q4 + 3]; sB[q4] = hl[4 * q4 + 3];
;                 } else {
;                     hl[4 * q4 + 3] = bv[4 * q4 + 3]; cp[4 * q4 + 3] = av[4 * q4 + 3];
; #pragma unroll
;                     for (int i = 2; i >= 0; --i) { hl[4 * q4 + i] = av[4 * q4 + i] * hl[4 * q4 + i + 1] + bv[4 * q4 + i]; cp[4 * q4 + i] = av[4 * q4 + i] * cp[4 * q4 + i + 1]; }
;                     sA[q4] = cp[4 * q4]; sB[q4] = hl[4 * q4];
;                 }
;             }
;             float Ae[4], Be[4], Ao[4], Bo[4];
; #pragma unroll
;             for (int q4 = 0; q4 < 4; ++q4) {
;                 const float oA = shx(sA[q4], 32, lane), oB = shx(sB[q4], 32, lane);
;                 Ae[q4] = hh ? oA : sA[q4]; Be[q4] = hh ? oB : sB[q4]; Ao[q4] = hh ? sA[q4] : oA; Bo[q4] = hh ? sB[q4] : oB;
;             }
;             if (PASS == 1) {
;                 float c = 0.f, P = 1.f;
;                 if (d == 0) {
; #pragma unroll
;                     for (int q4 = 0; q4 < 4; ++q4) { c = Ae[q4] * c + Be[q4]; c = Ao[q4] * c + Bo[q4]; P *= Ae[q4] * Ao[q4]; } }
;                 else {
; #pragma unroll
	v_exp_f32_e32 v14, v14
	v_rcp_f32_e32 v19, v19
	v_add_f32_e32 v17, v17, v80
	v_add_f32_e32 v13, 1.0, v13
	v_max_f32_e32 v87, 0xda24260, v87
	v_mul_f32_e32 v31, v84, v31
	v_exp_f32_e32 v17, v17
	v_mul_f32_e32 v90, v13, v87
	v_add_f32_e32 v15, v15, v81
	v_exp_f32_e32 v31, v31
	v_add_f32_e32 v18, 1.0, v18
	v_mul_f32_e32 v13, v13, v90
	v_fma_f32 v90, -v30, v30, 1.0
	v_exp_f32_e32 v15, v15
	v_rcp_f32_e32 v18, v18
	v_add_f32_e32 v16, 1.0, v16
	v_add_f32_e32 v14, 1.0, v14
	v_max_f32_e32 v90, 0xda24260, v90
	v_mul_f32_e32 v19, v84, v19
	v_rcp_f32_e32 v16, v16
	v_rsq_f32_e32 v13, v13
	v_mul_f32_e32 v91, v14, v90
	v_exp_f32_e32 v19, v19
	v_add_f32_e32 v3, v3, v81
	v_add_f32_e32 v17, 1.0, v17
	v_mul_f32_e32 v14, v14, v91
	v_fma_f32 v91, -v31, v31, 1.0
	v_exp_f32_e32 v3, v3
	v_rcp_f32_e32 v17, v17
	v_rsq_f32_e32 v14, v14
	v_add_f32_e32 v15, 1.0, v15
	v_max_f32_e32 v91, 0xda24260, v91
	v_mul_f32_e32 v18, v84, v18
	v_mul_f32_e32 v92, v15, v91
	v_exp_f32_e32 v18, v18
	v_add_f32_e32 v2, v2, v81
	v_mul_f32_e32 v16, v84, v16
	v_mul_f32_e32 v15, v15, v92
	v_mul_f32_e32 v13, v87, v13
	v_fma_f32 v87, -v19, v19, 1.0
	v_exp_f32_e32 v2, v2
	v_exp_f32_e32 v16, v16
	v_add_f32_e32 v0, v0, v81
	v_rsq_f32_e32 v15, v15
	v_max_f32_e32 v87, 0xda24260, v87
	v_add_f32_e32 v3, 1.0, v3
	v_mul_f32_e32 v17, v84, v17
	v_exp_f32_e32 v0, v0
	v_mul_f32_e32 v14, v90, v14
	v_mul_f32_e32 v90, v3, v87
	v_exp_f32_e32 v17, v17
	v_add_f32_e32 v1, v1, v81
	v_mul_f32_e32 v3, v3, v90
	v_fma_f32 v90, -v18, v18, 1.0
	v_exp_f32_e32 v1, v1
	v_max_f32_e32 v90, 0xda24260, v90
	v_add_f32_e32 v2, 1.0, v2
	v_fma_f32 v81, -v16, v16, 1.0
	v_mul_f32_e32 v15, v91, v15
	v_mul_f32_e32 v91, v2, v90
	v_max_f32_e32 v81, 0xda24260, v81
	v_add_f32_e32 v0, 1.0, v0
	v_mul_f32_e32 v2, v2, v91
	v_fma_f32 v91, -v17, v17, 1.0
	v_mul_f32_e32 v84, v0, v81
	v_max_f32_e32 v80, 0xda24260, v91
	v_add_f32_e32 v1, 1.0, v1
	v_mul_f32_e32 v0, v0, v84
	v_mul_f32_e32 v91, v1, v80
	v_rsq_f32_e32 v0, v0
	v_mul_f32_e32 v1, v1, v91
	v_rsq_f32_e32 v1, v1
	v_rsq_f32_e32 v2, v2
	v_mul_f32_e32 v0, v81, v0
	v_mul_f32_e32 v0, v59, v0
	v_mul_f32_e32 v1, v80, v1
	v_mul_f32_e32 v0, v17, v0
	v_fmac_f32_e32 v0, v65, v1
	v_mul_f32_e32 v2, v90, v2
	v_mul_f32_e32 v0, v18, v0
	v_mul_f32_e32 v4, v51, v4
	v_fmac_f32_e32 v0, v69, v2
	v_mul_f32_e32 v2, v19, v0
	v_mul_f32_e32 v0, v21, v4
	v_fmac_f32_e32 v0, v61, v5
	v_rsq_f32_e32 v3, v3
	v_mul_f32_e32 v0, v22, v0
	v_mul_f32_e32 v8, v53, v8
	v_fmac_f32_e32 v0, v67, v6
	v_mul_f32_e32 v4, v23, v0
	v_mul_f32_e32 v0, v25, v8
	v_mul_f32_e32 v1, v16, v17
	v_fmac_f32_e32 v0, v57, v9
	v_mul_f32_e32 v3, v87, v3
	v_mul_f32_e32 v1, v18, v1
	v_mul_f32_e32 v0, v26, v0
	v_mul_f32_e32 v12, v49, v12
	v_fmac_f32_e32 v2, v73, v3
	v_mul_f32_e32 v3, v19, v1
	v_mul_f32_e32 v1, v20, v21
	v_fmac_f32_e32 v0, v63, v10
	v_mul_f32_e32 v1, v22, v1
	v_mul_f32_e32 v6, v27, v0
	v_mul_f32_e32 v0, v29, v12
	v_mul_f32_e32 v5, v23, v1
	v_mul_f32_e32 v1, v24, v25
	v_fmac_f32_e32 v0, v55, v13
	v_mul_f32_e32 v1, v26, v1
	v_mul_f32_e32 v0, v30, v0
	v_fmac_f32_e32 v4, v79, v7
	v_mul_f32_e32 v7, v27, v1
	v_mul_f32_e32 v1, v28, v29
	v_fmac_f32_e32 v0, v71, v14
	v_mul_f32_e32 v1, v30, v1
	v_mul_f32_e32 v8, v31, v0
	v_fmac_f32_e32 v6, v77, v11
	v_fmac_f32_e32 v8, v75, v15
	v_mul_f32_e32 v9, v31, v1
	s_nop 1
	v_permlane32_swap_b32 v3, v16
	v_permlane32_swap_b32 v2, v15
	v_permlane32_swap_b32 v5, v14
	v_permlane32_swap_b32 v4, v13
	v_permlane32_swap_b32 v7, v12
	v_permlane32_swap_b32 v6, v11
	v_permlane32_swap_b32 v9, v10
	v_permlane32_swap_b32 v8, v1
	v_or_b32_e32 v0, 32, v110
	v_lshl_or_b32 v84, v0, 3, s79
	s_and_saveexec_b64 s[12:13], vcc
	s_cbranch_execz .LBB0_706
	v_fmac_f32_e32 v2, 0, v3
	s_waitcnt lgkmcnt(0)
	v_fmac_f32_e32 v15, v2, v16
	v_fmac_f32_e32 v4, v5, v15
	v_fmac_f32_e32 v13, v4, v14
	v_mul_f32_e32 v0, v3, v16
	v_mul_f32_e32 v17, v5, v14
	v_fmac_f32_e32 v6, v7, v13
	v_mul_f32_e32 v0, v0, v17
	v_mul_f32_e32 v17, v7, v12
	v_fmac_f32_e32 v11, v6, v12
	s_lshl_b64 s[10:11], s[10:11], 2
	v_mul_f32_e32 v0, v17, v0
	v_mul_f32_e32 v17, v9, v10
	v_fmac_f32_e32 v8, v9, v11
	s_add_u32 s10, s19, s10
	v_mul_f32_e32 v0, v17, v0
	v_fmac_f32_e32 v1, v8, v10
	s_addc_u32 s11, s30, s11
	global_store_dwordx2 v84, v[0:1], s[10:11]
.LBB0_706:
	s_or_b64 exec, exec, s[12:13]
	s_waitcnt lgkmcnt(0)
	s_addk_i32 s8, 0x208
	s_ashr_i32 s9, s8, 31
	s_lshl_b64 s[8:9], s[8:9], 11
	s_waitcnt lgkmcnt(0)
	v_mfma_f32_32x32x16_bf16 v[16:31], v[32:35], v[194:197], 0
	v_mfma_f32_32x32x16_bf16 v[16:31], v[36:39], v[198:201], v[16:31]
	s_waitcnt lgkmcnt(0)
	v_mfma_f32_32x32x16_bf16 v[16:31], v[40:43], v[202:205], v[16:31]
	v_mfma_f32_32x32x16_bf16 v[16:31], v[44:47], v[206:209], v[16:31]
	s_waitcnt lgkmcnt(0)
	v_mfma_f32_32x32x16_bf16 v[0:15], v[32:35], v[210:213], 0
	v_mfma_f32_32x32x16_bf16 v[0:15], v[36:39], v[214:217], v[0:15]
	ds_read2st64_b32 v[80:81], v83 offset0:147 offset1:148
	ds_read_b32 v87, v83 offset:38144
	s_waitcnt lgkmcnt(0)
; #define LAS __attribute__((address_space(3)))
; template <int PASS>
; __device__ __forceinline__ void lru_item(Frame& F, const LAS bf16* lw, const LAS float* prm, const LAS float* cwl, LAS float* xs, LAS unsigned char* pf, int head, int item, int nitem) {
;     ...
;                 const LAS bf16* wb = lw + ((d * 2 + gt) * 64 + t + 32 * ct) * LRU_WROW + 8 * hh;
; #pragma unroll
;                 for (int ks = 0; ks < 4; ++ks) a = __builtin_amdgcn_mfma_f32_32x32x16_bf16(af[ks], *(const LAS bf16x8*)(wb + 16 * ks), a, 0, 0, 0);
;                 acc[gt] = a;
;             }
;             const int chl = t + 32 * ct, ch = head * 64 + chl;
;             float av[16], bv[16];
;             {
;                 const float br = prm[(d * 3 + 0) * 64 + chl], bi = prm[(d * 3 + 1) * 64 + chl], c8 = prm[(d * 3 + 2) * 64 + chl];
; #pragma unroll
;                 for (int rg = 0; rg < 16; ++rg) {
;                     const float rr = __builtin_amdgcn_rcpf(1.f + __builtin_amdgcn_exp2f(acc[0][rg] + br)), ei = 1.f + __builtin_amdgcn_exp2f(acc[1][rg] + bi);
;                     const float a = __builtin_amdgcn_exp2f(c8 * rr), om = fmaxf(fmaf(-a, a, 1.f), 1e-30f);
;                     av[rg] = a; bv[rg] = (om * __builtin_amdgcn_rsqf(om * ei * ei)) * xd[ct][rg];
;                 }
	s_nop 3
	v_add_f32_e32 v20, v20, v80
	v_exp_f32_e32 v20, v20
	v_add_f32_e32 v22, v22, v80
	v_exp_f32_e32 v22, v22
	v_mfma_f32_32x32x16_bf16 v[0:15], v[40:43], v[218:221], v[0:15]
	v_add_f32_e32 v20, 1.0, v20
	v_rcp_f32_e32 v20, v20
	v_add_f32_e32 v18, v18, v80
	v_exp_f32_e32 v18, v18
	v_add_f32_e32 v16, v16, v80
	v_mul_f32_e32 v20, v87, v20
	v_exp_f32_e32 v90, v20
	v_mfma_f32_32x32x16_bf16 v[0:15], v[44:47], v[222:225], v[0:15]
	ds_read_b128 v[194:197], v226 offset:23040
	ds_read_b128 v[198:201], v226 offset:23072
	ds_read_b128 v[202:205], v226 offset:23104
	ds_read_b128 v[206:209], v226 offset:23136
	ds_read_b128 v[210:213], v226 offset:32256
	ds_read_b128 v[214:217], v226 offset:32288
	ds_read_b128 v[218:221], v226 offset:32320
	ds_read_b128 v[222:225], v226 offset:32352
	v_add_f32_e32 v20, v21, v80
	v_exp_f32_e32 v20, v20
	v_fma_f32 v21, -v90, v90, 1.0
	v_max_f32_e32 v21, 0xda24260, v21
	v_add_f32_e32 v18, 1.0, v18
	v_add_f32_e32 v20, 1.0, v20
	v_rcp_f32_e32 v20, v20
	s_nop 4
	v_add_f32_e32 v4, v4, v81
	v_exp_f32_e32 v4, v4
	v_add_f32_e32 v5, v5, v81
	v_mul_f32_e32 v20, v87, v20
	v_exp_f32_e32 v92, v20
	v_add_f32_e32 v4, 1.0, v4
	v_mul_f32_e32 v91, v4, v21
	v_exp_f32_e32 v5, v5
	v_mul_f32_e32 v4, v4, v91
	v_rsq_f32_e32 v4, v4
	v_fma_f32 v20, -v92, v92, 1.0
	v_add_f32_e32 v5, 1.0, v5
	v_max_f32_e32 v20, 0xda24260, v20
	v_mul_f32_e32 v91, v5, v20
	v_mul_f32_e32 v5, v5, v91
	v_mul_f32_e32 v91, v21, v4
	v_add_f32_e32 v4, 1.0, v22
	v_rcp_f32_e32 v4, v4
	v_rsq_f32_e32 v5, v5
	v_add_f32_e32 v7, v7, v81
	v_exp_f32_e32 v7, v7
	v_mul_f32_e32 v4, v87, v4
	v_exp_f32_e32 v93, v4
	v_add_f32_e32 v4, v23, v80
	v_exp_f32_e32 v4, v4
	v_mul_f32_e32 v22, v20, v5
	v_add_f32_e32 v5, v6, v81
	v_exp_f32_e32 v5, v5
	v_add_f32_e32 v4, 1.0, v4
	v_rcp_f32_e32 v4, v4
	v_fma_f32 v6, -v93, v93, 1.0
	v_add_f32_e32 v5, 1.0, v5
	v_max_f32_e32 v6, 0xda24260, v6
	v_mul_f32_e32 v4, v87, v4
	v_exp_f32_e32 v23, v4
	v_mul_f32_e32 v20, v5, v6
	v_mul_f32_e32 v4, v5, v20
	v_add_f32_e32 v20, v24, v80
	v_rsq_f32_e32 v5, v4
	v_add_f32_e32 v4, 1.0, v7
	v_fma_f32 v7, -v23, v23, 1.0
	v_exp_f32_e32 v20, v20
	v_max_f32_e32 v7, 0xda24260, v7
	v_mul_f32_e32 v21, v4, v7
	v_mul_f32_e32 v4, v4, v21
	v_add_f32_e32 v20, 1.0, v20
	v_rsq_f32_e32 v21, v4
	v_add_f32_e32 v4, v8, v81
	v_rcp_f32_e32 v20, v20
	v_exp_f32_e32 v8, v4
	v_mul_f32_e32 v24, v6, v5
	v_mul_f32_e32 v5, v7, v21
	v_mul_f32_e32 v4, v87, v20
	v_add_f32_e32 v6, 1.0, v8
	v_add_f32_e32 v8, v25, v80
	v_exp_f32_e32 v4, v4
	v_exp_f32_e32 v8, v8
	v_mul_f32_e32 v25, v78, v5
	v_add_f32_e32 v11, v11, v81
	v_fma_f32 v7, -v4, v4, 1.0
	v_add_f32_e32 v8, 1.0, v8
	v_max_f32_e32 v7, 0xda24260, v7
	v_rcp_f32_e32 v8, v8
	v_mul_f32_e32 v20, v6, v7
	v_mul_f32_e32 v6, v6, v20
	v_rsq_f32_e32 v20, v6
	v_add_f32_e32 v6, v9, v81
	v_exp_f32_e32 v9, v6
	v_mul_f32_e32 v6, v87, v8
	v_exp_f32_e32 v6, v6
	v_add_f32_e32 v8, v26, v80
	v_exp_f32_e32 v8, v8
	v_mul_f32_e32 v78, v7, v20
	v_fma_f32 v7, -v6, v6, 1.0
	v_add_f32_e32 v5, 1.0, v9
	v_max_f32_e32 v7, 0xda24260, v7
	v_mul_f32_e32 v9, v5, v7
	v_mul_f32_e32 v5, v5, v9
	v_add_f32_e32 v8, 1.0, v8
	v_add_f32_e32 v9, v10, v81
	v_add_f32_e32 v10, v27, v80
	v_rcp_f32_e32 v8, v8
	v_exp_f32_e32 v10, v10
	v_exp_f32_e32 v9, v9
	v_exp_f32_e32 v11, v11
	v_mul_f32_e32 v8, v87, v8
	v_add_f32_e32 v10, 1.0, v10
	v_exp_f32_e32 v8, v8
	v_rcp_f32_e32 v10, v10
	v_add_f32_e32 v9, 1.0, v9
	v_rsq_f32_e32 v5, v5
	v_fma_f32 v20, -v8, v8, 1.0
	v_mul_f32_e32 v10, v87, v10
	v_max_f32_e32 v21, 0xda24260, v20
	v_exp_f32_e32 v20, v10
	v_add_f32_e32 v10, 1.0, v11
	v_mul_f32_e32 v26, v9, v21
	v_mul_f32_e32 v9, v9, v26
	v_fma_f32 v11, -v20, v20, 1.0
	v_max_f32_e32 v11, 0xda24260, v11
	v_mul_f32_e32 v26, v10, v11
	v_mul_f32_e32 v10, v10, v26
	v_add_f32_e32 v26, v28, v80
	v_exp_f32_e32 v26, v26
	v_rsq_f32_e32 v10, v10
	v_mul_f32_e32 v27, v7, v5
	v_rsq_f32_e32 v9, v9
	v_add_f32_e32 v7, 1.0, v26
	v_rcp_f32_e32 v7, v7
	v_mul_f32_e32 v5, v11, v10
	v_mul_f32_e32 v26, v76, v5
	v_add_f32_e32 v5, v12, v81
	v_mul_f32_e32 v28, v21, v9
	v_exp_f32_e32 v9, v5
	v_mul_f32_e32 v5, v87, v7
	v_add_f32_e32 v7, v29, v80
	v_exp_f32_e32 v7, v7
	v_exp_f32_e32 v5, v5
	v_add_f32_e32 v12, v13, v81
	v_exp_f32_e32 v12, v12
	v_add_f32_e32 v7, 1.0, v7
	v_rcp_f32_e32 v7, v7
	v_fma_f32 v10, -v5, v5, 1.0
	v_add_f32_e32 v9, 1.0, v9
	v_max_f32_e32 v10, 0xda24260, v10
	v_mul_f32_e32 v7, v87, v7
	v_exp_f32_e32 v7, v7
	v_mul_f32_e32 v11, v9, v10
	v_add_f32_e32 v13, v30, v80
	v_mul_f32_e32 v9, v9, v11
	v_exp_f32_e32 v13, v13
	v_rsq_f32_e32 v11, v9
	v_add_f32_e32 v9, 1.0, v12
	v_fma_f32 v12, -v7, v7, 1.0
	v_max_f32_e32 v12, 0xda24260, v12
	v_mul_f32_e32 v21, v9, v12
	v_mul_f32_e32 v9, v9, v21
	v_add_f32_e32 v13, 1.0, v13
	v_rcp_f32_e32 v13, v13
	v_rsq_f32_e32 v21, v9
	v_add_f32_e32 v9, v14, v81
	v_exp_f32_e32 v14, v9
	v_mul_f32_e32 v9, v87, v13
	v_mul_f32_e32 v13, v12, v21
	v_add_f32_e32 v12, v31, v80
	v_exp_f32_e32 v12, v12
	v_exp_f32_e32 v9, v9
	v_mul_f32_e32 v29, v10, v11
	v_add_f32_e32 v10, 1.0, v14
	v_add_f32_e32 v12, 1.0, v12
	v_rcp_f32_e32 v12, v12
	v_fma_f32 v11, -v9, v9, 1.0
	v_max_f32_e32 v11, 0xda24260, v11
	v_mul_f32_e32 v14, v10, v11
	v_mul_f32_e32 v10, v10, v14
	v_mul_f32_e32 v12, v87, v12
	v_rsq_f32_e32 v10, v10
	v_add_f32_e32 v14, v15, v81
	v_exp_f32_e32 v21, v12
	v_exp_f32_e32 v14, v14
	v_add_f32_e32 v12, v19, v80
	v_exp_f32_e32 v12, v12
	v_mul_f32_e32 v15, v11, v10
	v_fma_f32 v11, -v21, v21, 1.0
	v_add_f32_e32 v10, 1.0, v14
	v_max_f32_e32 v11, 0xda24260, v11
	v_add_f32_e32 v12, 1.0, v12
	v_mul_f32_e32 v14, v10, v11
	v_rcp_f32_e32 v12, v12
	v_mul_f32_e32 v10, v10, v14
	v_rsq_f32_e32 v10, v10
	v_add_f32_e32 v3, v3, v81
	v_mul_f32_e32 v12, v87, v12
	v_exp_f32_e32 v12, v12
; #define LAS __attribute__((address_space(3)))
; template <int PASS>
; __device__ __forceinline__ void lru_item(Frame& F, const LAS bf16* lw, const LAS float* prm, const LAS float* cwl, LAS float* xs, LAS unsigned char* pf, int head, int item, int nitem) {
;     ...
;                 const LAS bf16* wb = lw + ((d * 2 + gt) * 64 + t + 32 * ct) * LRU_WROW + 8 * hh;
; #pragma unroll
;                 for (int ks = 0; ks < 4; ++ks) a = __builtin_amdgcn_mfma_f32_32x32x16_bf16(af[ks], *(const LAS bf16x8*)(wb + 16 * ks), a, 0, 0, 0);
;                 acc[gt] = a;
;             }
;             const int chl = t + 32 * ct, ch = head * 64 + chl;
;             float av[16], bv[16];
;             {
;                 const float br = prm[(d * 3 + 0) * 64 + chl], bi = prm[(d * 3 + 1) * 64 + chl], c8 = prm[(d * 3 + 2) * 64 + chl];
; #pragma unroll
;                 for (int rg = 0; rg < 16; ++rg) {
;                     const float rr = __builtin_amdgcn_rcpf(1.f + __builtin_amdgcn_exp2f(acc[0][rg] + br)), ei = 1.f + __builtin_amdgcn_exp2f(acc[1][rg] + bi);
;                     const float a = __builtin_amdgcn_exp2f(c8 * rr), om = fmaxf(fmaf(-a, a, 1.f), 1e-30f);
;                     av[rg] = a; bv[rg] = (om * __builtin_amdgcn_rsqf(om * ei * ei)) * xd[ct][rg];
;                 }
;             }
;             float hl[16], cp[16], sA[4], sB[4];
; #pragma unroll
;             for (int q4 = 0; q4 < 4; ++q4) {
;                 if (d == 0) {
;                     hl[4 * q4] = bv[4 * q4]; cp[4 * q4] = av[4 * q4];
; #pragma unroll
;                     for (int i = 1; i < 4; ++i) { hl[4 * q4 + i] = av[4 * q4 + i] * hl[4 * q4 + i - 1] + bv[4 * q4 + i]; cp[4 * q4 + i] = av[4 * q4 + i] * cp[4 * q4 + i - 1]; }
;                     sA[q4] = cp[4 * q4 + 3]; sB[q4] = hl[4 * q4 + 3];
;                 } else {
;                     hl[4 * q4 + 3] = bv[4 * q4 + 3]; cp[4 * q4 + 3] = av[4 * q4 + 3];
; #pragma unroll
;                     for (int i = 2; i >= 0; --i) { hl[4 * q4 + i] = av[4 * q4 + i] * hl[4 * q4 + i + 1] + bv[4 * q4 + i]; cp[4 * q4 + i] = av[4 * q4 + i] * cp[4 * q4 + i + 1]; }
;                     sA[q4] = cp[4 * q4]; sB[q4] = hl[4 * q4];
;                 }
;             }
;             float Ae[4], Be[4], Ao[4], Bo[4];
; #pragma unroll
;             for (int q4 = 0; q4 < 4; ++q4) {
;                 const float oA = shx(sA[q4], 32, lane), oB = shx(sB[q4], 32, lane);
	v_mul_f32_e32 v10, v11, v10
	v_add_f32_e32 v11, v17, v80
	v_exp_f32_e32 v3, v3
	v_exp_f32_e32 v11, v11
	v_rcp_f32_e32 v18, v18
	v_fma_f32 v14, -v12, v12, 1.0
	v_exp_f32_e32 v16, v16
	v_max_f32_e32 v14, 0xda24260, v14
	v_add_f32_e32 v3, 1.0, v3
	v_add_f32_e32 v11, 1.0, v11
	v_mul_f32_e32 v19, v3, v14
	v_rcp_f32_e32 v11, v11
	v_mul_f32_e32 v3, v3, v19
	v_mul_f32_e32 v19, v74, v10
	v_mul_f32_e32 v10, v87, v18
	v_rsq_f32_e32 v3, v3
	v_exp_f32_e32 v10, v10
	v_add_f32_e32 v2, v2, v81
	v_add_f32_e32 v16, 1.0, v16
	v_exp_f32_e32 v2, v2
	v_rcp_f32_e32 v16, v16
	v_mul_f32_e32 v11, v87, v11
	v_exp_f32_e32 v11, v11
	v_add_f32_e32 v1, v1, v81
	v_mul_f32_e32 v3, v14, v3
	v_fma_f32 v14, -v10, v10, 1.0
	v_exp_f32_e32 v1, v1
	v_max_f32_e32 v14, 0xda24260, v14
	v_add_f32_e32 v2, 1.0, v2
	v_mul_f32_e32 v16, v87, v16
	v_mul_f32_e32 v17, v2, v14
	v_exp_f32_e32 v16, v16
	v_add_f32_e32 v0, v0, v81
	v_mul_f32_e32 v2, v2, v17
	v_fma_f32 v17, -v11, v11, 1.0
	v_exp_f32_e32 v0, v0
	v_max_f32_e32 v17, 0xda24260, v17
	v_add_f32_e32 v1, 1.0, v1
	v_mul_f32_e32 v18, v1, v17
	v_rsq_f32_e32 v2, v2
	v_mul_f32_e32 v1, v1, v18
	v_fma_f32 v18, -v16, v16, 1.0
	v_max_f32_e32 v18, 0xda24260, v18
	v_add_f32_e32 v0, 1.0, v0
	v_rsq_f32_e32 v1, v1
	v_mul_f32_e32 v30, v0, v18
	v_mul_f32_e32 v0, v0, v30
	v_mul_f32_e32 v3, v72, v3
	v_rsq_f32_e32 v0, v0
	v_mul_f32_e32 v2, v14, v2
	v_mul_f32_e32 v3, v10, v3
	v_fmac_f32_e32 v3, v68, v2
	v_mul_f32_e32 v1, v17, v1
	v_mul_f32_e32 v3, v11, v3
	v_fmac_f32_e32 v3, v64, v1
	v_mul_f32_e32 v0, v18, v0
	v_mul_f32_e32 v1, v16, v3
	v_fmac_f32_e32 v1, v58, v0
	v_mul_f32_e32 v0, v93, v25
	v_fmac_f32_e32 v0, v66, v24
	v_mul_f32_e32 v0, v92, v0
	v_fmac_f32_e32 v0, v60, v22
	v_mul_f32_e32 v2, v12, v10
	v_mul_f32_e32 v10, v90, v0
	v_mul_f32_e32 v0, v8, v26
	v_fmac_f32_e32 v0, v62, v28
	v_mul_f32_e32 v0, v6, v0
	v_fmac_f32_e32 v0, v56, v27
	v_mul_f32_e32 v12, v4, v0
	v_mul_f32_e32 v0, v9, v19
	v_fmac_f32_e32 v0, v70, v15
	v_mul_f32_e32 v2, v11, v2
	v_mul_f32_e32 v0, v7, v0
	v_mul_f32_e32 v3, v16, v2
	v_mul_f32_e32 v2, v23, v93
	v_fmac_f32_e32 v0, v54, v13
	v_pk_mul_f32 v[8:9], v[20:21], v[8:9]
	v_mul_f32_e32 v2, v92, v2
	v_mul_f32_e32 v13, v5, v0
	v_pk_mul_f32 v[6:7], v[6:7], v[8:9]
	v_fmac_f32_e32 v10, v50, v91
	v_mul_f32_e32 v11, v90, v2
	v_fmac_f32_e32 v12, v52, v78
	v_fmac_f32_e32 v13, v48, v29
	v_pk_mul_f32 v[6:7], v[4:5], v[6:7]
	s_nop 1
	v_permlane32_swap_b32 v3, v4
	v_permlane32_swap_b32 v1, v5
	v_permlane32_swap_b32 v11, v15
	v_permlane32_swap_b32 v10, v14
	v_permlane32_swap_b32 v6, v8
	v_permlane32_swap_b32 v12, v16
	v_permlane32_swap_b32 v7, v9
	v_permlane32_swap_b32 v13, v17
	s_and_saveexec_b64 s[10:11], vcc
	s_cbranch_execz .LBB0_708
	s_waitcnt lgkmcnt(0)
	v_fmac_f32_e32 v17, 0, v9
	v_fmac_f32_e32 v13, v7, v17
	v_fmac_f32_e32 v16, v13, v8
	v_fmac_f32_e32 v12, v6, v16
	v_pk_mul_f32 v[18:19], v[6:7], v[8:9]
	v_fmac_f32_e32 v14, v12, v15
	v_mul_f32_e32 v2, v11, v15
	v_fmac_f32_e32 v10, v11, v14
	s_lshl_b64 s[12:13], s[8:9], 2
	v_pk_mul_f32 v[8:9], v[18:19], v[18:19] op_sel:[0,1] op_sel_hi:[1,0]
	v_mul_f32_e32 v0, v3, v4
	v_fmac_f32_e32 v5, v10, v4
	s_add_u32 s12, s19, s12
	v_mov_b32_e32 v4, v8
	v_pk_mul_f32 v[8:9], v[2:3], v[8:9]
	s_addc_u32 s13, s30, s13
	v_pk_mul_f32 v[8:9], v[0:1], v[8:9]
	v_pk_fma_f32 v[0:1], v[2:3], v[4:5], v[0:1]
	v_lshl_add_u64 v[6:7], v[88:89], 2, s[12:13]
	v_mov_b32_e32 v9, v1
	global_store_dwordx2 v[6:7], v[8:9], off
.LBB0_708:
	s_or_b64 exec, exec, s[10:11]
	ds_read_b32 v48, v83 offset:38272
	s_waitcnt lgkmcnt(0)
	v_mfma_f32_32x32x16_bf16 v[16:31], v[32:35], v[194:197], 0
	s_waitcnt lgkmcnt(0)
	v_mfma_f32_32x32x16_bf16 v[16:31], v[36:39], v[198:201], v[16:31]
	v_mfma_f32_32x32x16_bf16 v[16:31], v[40:43], v[202:205], v[16:31]
	s_waitcnt lgkmcnt(0)
	v_mfma_f32_32x32x16_bf16 v[16:31], v[44:47], v[206:209], v[16:31]
	v_mfma_f32_32x32x16_bf16 v[0:15], v[32:35], v[210:213], 0
	s_waitcnt lgkmcnt(0)
	v_mfma_f32_32x32x16_bf16 v[0:15], v[36:39], v[214:217], v[0:15]
	ds_read2st64_b32 v[32:33], v86 offset0:147 offset1:148
	s_waitcnt lgkmcnt(0)
	s_nop 3
	v_add_f32_e32 v20, v20, v32
	v_exp_f32_e32 v20, v20
	v_mfma_f32_32x32x16_bf16 v[0:15], v[40:43], v[218:221], v[0:15]
	v_add_f32_e32 v22, v22, v32
	v_exp_f32_e32 v22, v22
	v_add_f32_e32 v20, 1.0, v20
	v_rcp_f32_e32 v20, v20
	v_add_f32_e32 v18, v18, v32
	v_exp_f32_e32 v18, v18
	v_add_f32_e32 v16, v16, v32
	v_mfma_f32_32x32x16_bf16 v[0:15], v[44:47], v[222:225], v[0:15]
	v_mul_f32_e32 v20, v48, v20
	v_exp_f32_e32 v34, v20
	v_add_f32_e32 v20, v21, v32
	v_exp_f32_e32 v20, v20
	v_add_f32_e32 v18, 1.0, v18
	v_fma_f32 v21, -v34, v34, 1.0
	v_max_f32_e32 v21, 0xda24260, v21
	v_add_f32_e32 v20, 1.0, v20
	s_nop 3
	v_add_f32_e32 v4, v4, v33
	v_rcp_f32_e32 v20, v20
	v_exp_f32_e32 v4, v4
	v_add_f32_e32 v5, v5, v33
	v_exp_f32_e32 v5, v5
	v_mul_f32_e32 v20, v48, v20
	v_add_f32_e32 v4, 1.0, v4
	v_exp_f32_e32 v36, v20
	v_mul_f32_e32 v35, v4, v21
	v_mul_f32_e32 v4, v4, v35
	v_rsq_f32_e32 v4, v4
	v_fma_f32 v20, -v36, v36, 1.0
	v_add_f32_e32 v5, 1.0, v5
	v_max_f32_e32 v20, 0xda24260, v20
	v_mul_f32_e32 v35, v5, v20
	v_mul_f32_e32 v5, v5, v35
	v_mul_f32_e32 v35, v21, v4
	v_add_f32_e32 v4, 1.0, v22
	v_rcp_f32_e32 v4, v4
	v_rsq_f32_e32 v5, v5
	v_add_f32_e32 v7, v7, v33
	v_exp_f32_e32 v7, v7
	v_mul_f32_e32 v4, v48, v4
	v_exp_f32_e32 v37, v4
	v_add_f32_e32 v4, v23, v32
	v_exp_f32_e32 v4, v4
	v_mul_f32_e32 v22, v20, v5
	v_add_f32_e32 v5, v6, v33
	v_exp_f32_e32 v5, v5
	v_add_f32_e32 v4, 1.0, v4
	v_rcp_f32_e32 v4, v4
	v_fma_f32 v6, -v37, v37, 1.0
	v_add_f32_e32 v5, 1.0, v5
	v_max_f32_e32 v6, 0xda24260, v6
	v_mul_f32_e32 v4, v48, v4
	v_exp_f32_e32 v23, v4
	v_mul_f32_e32 v20, v5, v6
	v_mul_f32_e32 v4, v5, v20
; template <int PASS>
; __device__ __forceinline__ void lru_item(Frame& F, const LAS bf16* lw, const LAS float* prm, const LAS float* cwl, LAS float* xs, LAS unsigned char* pf, int head, int item, int nitem) {
;     ...
;                 const float br = prm[(d * 3 + 0) * 64 + chl], bi = prm[(d * 3 + 1) * 64 + chl], c8 = prm[(d * 3 + 2) * 64 + chl];
; #pragma unroll
;                 for (int rg = 0; rg < 16; ++rg) {
;                     const float rr = __builtin_amdgcn_rcpf(1.f + __builtin_amdgcn_exp2f(acc[0][rg] + br)), ei = 1.f + __builtin_amdgcn_exp2f(acc[1][rg] + bi);
;                     const float a = __builtin_amdgcn_exp2f(c8 * rr), om = fmaxf(fmaf(-a, a, 1.f), 1e-30f);
;                     av[rg] = a; bv[rg] = (om * __builtin_amdgcn_rsqf(om * ei * ei)) * xd[ct][rg];
;                 }
;             }
;             float hl[16], cp[16], sA[4], sB[4];
; #pragma unroll
;             for (int q4 = 0; q4 < 4; ++q4) {
;                 if (d == 0) {
;                     hl[4 * q4] = bv[4 * q4]; cp[4 * q4] = av[4 * q4];
; #pragma unroll
;                     for (int i = 1; i < 4; ++i) { hl[4 * q4 + i] = av[4 * q4 + i] * hl[4 * q4 + i - 1] + bv[4 * q4 + i]; cp[4 * q4 + i] = av[4 * q4 + i] * cp[4 * q4 + i - 1]; }
;                     sA[q4] = cp[4 * q4 + 3]; sB[q4] = hl[4 * q4 + 3];
;                 } else {
;                     hl[4 * q4 + 3] = bv[4 * q4 + 3]; cp[4 * q4 + 3] = av[4 * q4 + 3];
; #pragma unroll
;                     for (int i = 2; i >= 0; --i) { hl[4 * q4 + i] = av[4 * q4 + i] * hl[4 * q4 + i + 1] + bv[4 * q4 + i]; cp[4 * q4 + i] = av[4 * q4 + i] * cp[4 * q4 + i + 1]; }
;                     sA[q4] = cp[4 * q4]; sB[q4] = hl[4 * q4];
;                 }
;             }
;             float Ae[4], Be[4], Ao[4], Bo[4];
; #pragma unroll
;             for (int q4 = 0; q4 < 4; ++q4) {
;                 const float oA = shx(sA[q4], 32, lane), oB = shx(sB[q4], 32, lane);
;                 Ae[q4] = hh ? oA : sA[q4]; Be[q4] = hh ? oB : sB[q4]; Ao[q4] = hh ? sA[q4] : oA; Bo[q4] = hh ? sB[q4] : oB;
;             }
;             if (PASS == 1) {
;                 float c = 0.f, P = 1.f;
;                 if (d == 0) {
; #pragma unroll
;                     for (int q4 = 0; q4 < 4; ++q4) { c = Ae[q4] * c + Be[q4]; c = Ao[q4] * c + Bo[q4]; P *= Ae[q4] * Ao[q4]; } }
;                 else {
; #pragma unroll
	v_add_f32_e32 v20, v24, v32
	v_rsq_f32_e32 v5, v4
	v_add_f32_e32 v4, 1.0, v7
	v_fma_f32 v7, -v23, v23, 1.0
	v_exp_f32_e32 v20, v20
	v_max_f32_e32 v7, 0xda24260, v7
	v_mul_f32_e32 v21, v4, v7
	v_mul_f32_e32 v4, v4, v21
	v_add_f32_e32 v20, 1.0, v20
	v_rsq_f32_e32 v21, v4
	v_add_f32_e32 v4, v8, v33
	v_rcp_f32_e32 v20, v20
	v_exp_f32_e32 v8, v4
	v_mul_f32_e32 v24, v6, v5
	v_mul_f32_e32 v5, v7, v21
	v_mul_f32_e32 v4, v48, v20
	v_add_f32_e32 v6, 1.0, v8
	v_add_f32_e32 v8, v25, v32
	v_exp_f32_e32 v4, v4
	v_exp_f32_e32 v8, v8
	v_mul_f32_e32 v25, v79, v5
	v_add_f32_e32 v11, v11, v33
	v_fma_f32 v7, -v4, v4, 1.0
	v_add_f32_e32 v8, 1.0, v8
	v_max_f32_e32 v7, 0xda24260, v7
	v_rcp_f32_e32 v8, v8
	v_mul_f32_e32 v20, v6, v7
	v_mul_f32_e32 v6, v6, v20
	v_rsq_f32_e32 v20, v6
	v_add_f32_e32 v6, v9, v33
	v_exp_f32_e32 v9, v6
	v_mul_f32_e32 v6, v48, v8
	v_exp_f32_e32 v6, v6
	v_add_f32_e32 v8, v26, v32
	v_exp_f32_e32 v8, v8
	v_mul_f32_e32 v38, v7, v20
	v_fma_f32 v7, -v6, v6, 1.0
	v_add_f32_e32 v5, 1.0, v9
	v_max_f32_e32 v7, 0xda24260, v7
	v_mul_f32_e32 v9, v5, v7
	v_mul_f32_e32 v5, v5, v9
	v_add_f32_e32 v8, 1.0, v8
	v_add_f32_e32 v9, v10, v33
	v_add_f32_e32 v10, v27, v32
	v_rcp_f32_e32 v8, v8
	v_exp_f32_e32 v10, v10
	v_exp_f32_e32 v9, v9
	v_exp_f32_e32 v11, v11
	v_mul_f32_e32 v8, v48, v8
	v_add_f32_e32 v10, 1.0, v10
	v_exp_f32_e32 v8, v8
	v_rcp_f32_e32 v10, v10
	v_add_f32_e32 v9, 1.0, v9
	v_rsq_f32_e32 v5, v5
	v_fma_f32 v20, -v8, v8, 1.0
	v_mul_f32_e32 v10, v48, v10
	v_max_f32_e32 v21, 0xda24260, v20
	v_exp_f32_e32 v20, v10
	v_add_f32_e32 v10, 1.0, v11
	v_mul_f32_e32 v26, v9, v21
	v_mul_f32_e32 v9, v9, v26
	v_fma_f32 v11, -v20, v20, 1.0
	v_max_f32_e32 v11, 0xda24260, v11
	v_mul_f32_e32 v26, v10, v11
	v_mul_f32_e32 v10, v10, v26
	v_add_f32_e32 v26, v28, v32
	v_exp_f32_e32 v26, v26
	v_rsq_f32_e32 v10, v10
	v_mul_f32_e32 v27, v7, v5
	v_rsq_f32_e32 v9, v9
	v_add_f32_e32 v7, 1.0, v26
	v_rcp_f32_e32 v7, v7
	v_mul_f32_e32 v5, v11, v10
	v_mul_f32_e32 v26, v77, v5
	v_add_f32_e32 v5, v12, v33
	v_mul_f32_e32 v28, v21, v9
	v_exp_f32_e32 v9, v5
	v_mul_f32_e32 v5, v48, v7
	v_add_f32_e32 v7, v29, v32
	v_exp_f32_e32 v7, v7
	v_exp_f32_e32 v5, v5
	v_add_f32_e32 v12, v13, v33
	v_exp_f32_e32 v12, v12
	v_add_f32_e32 v7, 1.0, v7
	v_rcp_f32_e32 v7, v7
	v_fma_f32 v10, -v5, v5, 1.0
	v_add_f32_e32 v9, 1.0, v9
	v_max_f32_e32 v10, 0xda24260, v10
	v_mul_f32_e32 v7, v48, v7
	v_exp_f32_e32 v7, v7
	v_mul_f32_e32 v11, v9, v10
	v_add_f32_e32 v13, v30, v32
	v_mul_f32_e32 v9, v9, v11
	v_exp_f32_e32 v13, v13
	v_rsq_f32_e32 v11, v9
	v_add_f32_e32 v9, 1.0, v12
	v_fma_f32 v12, -v7, v7, 1.0
	v_max_f32_e32 v12, 0xda24260, v12
	v_mul_f32_e32 v21, v9, v12
	v_mul_f32_e32 v9, v9, v21
	v_add_f32_e32 v13, 1.0, v13
	v_rcp_f32_e32 v13, v13
	v_rsq_f32_e32 v21, v9
	v_add_f32_e32 v9, v14, v33
	v_exp_f32_e32 v14, v9
	v_mul_f32_e32 v9, v48, v13
	v_mul_f32_e32 v13, v12, v21
	v_add_f32_e32 v12, v31, v32
	v_exp_f32_e32 v12, v12
	v_exp_f32_e32 v9, v9
	v_mul_f32_e32 v29, v10, v11
	v_add_f32_e32 v10, 1.0, v14
	v_add_f32_e32 v12, 1.0, v12
	v_rcp_f32_e32 v12, v12
	v_fma_f32 v11, -v9, v9, 1.0
	v_max_f32_e32 v11, 0xda24260, v11
	v_mul_f32_e32 v14, v10, v11
	v_mul_f32_e32 v10, v10, v14
	v_mul_f32_e32 v12, v48, v12
	v_rsq_f32_e32 v10, v10
	v_add_f32_e32 v14, v15, v33
	v_exp_f32_e32 v21, v12
	v_exp_f32_e32 v14, v14
	v_add_f32_e32 v12, v19, v32
	v_exp_f32_e32 v12, v12
	v_mul_f32_e32 v15, v11, v10
	v_fma_f32 v11, -v21, v21, 1.0
	v_add_f32_e32 v10, 1.0, v14
	v_max_f32_e32 v11, 0xda24260, v11
	v_add_f32_e32 v12, 1.0, v12
	v_mul_f32_e32 v14, v10, v11
	v_rcp_f32_e32 v12, v12
	v_mul_f32_e32 v10, v10, v14
	v_rsq_f32_e32 v10, v10
	v_add_f32_e32 v3, v3, v33
	v_mul_f32_e32 v12, v48, v12
	v_exp_f32_e32 v12, v12
	v_mul_f32_e32 v10, v11, v10
	v_add_f32_e32 v11, v17, v32
	v_exp_f32_e32 v3, v3
	v_exp_f32_e32 v11, v11
	v_rcp_f32_e32 v18, v18
	v_fma_f32 v14, -v12, v12, 1.0
	v_exp_f32_e32 v16, v16
	v_max_f32_e32 v14, 0xda24260, v14
	v_add_f32_e32 v3, 1.0, v3
	v_add_f32_e32 v11, 1.0, v11
	v_mul_f32_e32 v19, v3, v14
	v_rcp_f32_e32 v11, v11
	v_mul_f32_e32 v3, v3, v19
	v_mul_f32_e32 v19, v75, v10
	v_mul_f32_e32 v10, v48, v18
	v_rsq_f32_e32 v3, v3
	v_exp_f32_e32 v10, v10
	v_add_f32_e32 v2, v2, v33
	v_add_f32_e32 v16, 1.0, v16
	v_exp_f32_e32 v2, v2
	v_rcp_f32_e32 v16, v16
	v_mul_f32_e32 v11, v48, v11
	v_exp_f32_e32 v11, v11
	v_add_f32_e32 v1, v1, v33
	v_mul_f32_e32 v3, v14, v3
	v_fma_f32 v14, -v10, v10, 1.0
	v_exp_f32_e32 v1, v1
	v_max_f32_e32 v14, 0xda24260, v14
	v_add_f32_e32 v2, 1.0, v2
	v_mul_f32_e32 v16, v48, v16
	v_mul_f32_e32 v17, v2, v14
	v_exp_f32_e32 v16, v16
	v_add_f32_e32 v0, v0, v33
	v_mul_f32_e32 v2, v2, v17
	v_fma_f32 v17, -v11, v11, 1.0
	v_exp_f32_e32 v0, v0
	v_max_f32_e32 v17, 0xda24260, v17
	v_add_f32_e32 v1, 1.0, v1
	v_mul_f32_e32 v18, v1, v17
	v_rsq_f32_e32 v2, v2
	v_mul_f32_e32 v1, v1, v18
	v_fma_f32 v18, -v16, v16, 1.0
	v_max_f32_e32 v18, 0xda24260, v18
	v_add_f32_e32 v0, 1.0, v0
	v_rsq_f32_e32 v1, v1
	v_mul_f32_e32 v30, v0, v18
	v_mul_f32_e32 v0, v0, v30
	v_mul_f32_e32 v3, v73, v3
	v_rsq_f32_e32 v0, v0
	v_mul_f32_e32 v2, v14, v2
	v_mul_f32_e32 v3, v10, v3
	v_fmac_f32_e32 v3, v69, v2
	v_mul_f32_e32 v1, v17, v1
	v_mul_f32_e32 v3, v11, v3
	v_fmac_f32_e32 v3, v65, v1
	v_mul_f32_e32 v0, v18, v0
	v_mul_f32_e32 v1, v16, v3
	v_fmac_f32_e32 v1, v59, v0
	v_mul_f32_e32 v0, v37, v25
	v_fmac_f32_e32 v0, v67, v24
	v_mul_f32_e32 v0, v36, v0
	v_fmac_f32_e32 v0, v61, v22
	v_mul_f32_e32 v2, v12, v10
	v_mul_f32_e32 v10, v34, v0
	v_mul_f32_e32 v0, v8, v26
	v_fmac_f32_e32 v0, v63, v28
	v_mul_f32_e32 v0, v6, v0
	v_fmac_f32_e32 v0, v57, v27
	v_mul_f32_e32 v12, v4, v0
	v_mul_f32_e32 v0, v9, v19
	v_fmac_f32_e32 v0, v71, v15
	v_mul_f32_e32 v2, v11, v2
	v_mul_f32_e32 v0, v7, v0
	v_mul_f32_e32 v3, v16, v2
	v_mul_f32_e32 v2, v23, v37
	v_fmac_f32_e32 v0, v55, v13
	v_pk_mul_f32 v[8:9], v[20:21], v[8:9]
	v_mul_f32_e32 v2, v36, v2
	v_mul_f32_e32 v13, v5, v0
	v_pk_mul_f32 v[6:7], v[6:7], v[8:9]
	v_fmac_f32_e32 v10, v51, v35
	v_mul_f32_e32 v11, v34, v2
	v_fmac_f32_e32 v12, v53, v38
	v_fmac_f32_e32 v13, v49, v29
	v_pk_mul_f32 v[6:7], v[4:5], v[6:7]
	s_nop 1
	v_permlane32_swap_b32 v3, v4
	v_permlane32_swap_b32 v1, v5
	v_permlane32_swap_b32 v11, v15
	v_permlane32_swap_b32 v10, v14
	v_permlane32_swap_b32 v6, v8
	v_permlane32_swap_b32 v12, v16
	v_permlane32_swap_b32 v7, v9
	v_permlane32_swap_b32 v13, v17
	s_and_saveexec_b64 s[10:11], vcc
	s_cbranch_execz .LBB0_693
	s_waitcnt lgkmcnt(0)
	v_fmac_f32_e32 v17, 0, v9
	v_fmac_f32_e32 v13, v7, v17
	v_fmac_f32_e32 v16, v13, v8
	v_fmac_f32_e32 v12, v6, v16
	v_pk_mul_f32 v[18:19], v[6:7], v[8:9]
	v_fmac_f32_e32 v14, v12, v15
	v_mul_f32_e32 v2, v11, v15
	v_fmac_f32_e32 v10, v11, v14
	v_pk_mul_f32 v[6:7], v[18:19], v[18:19] op_sel:[0,1] op_sel_hi:[1,0]
	v_mul_f32_e32 v0, v3, v4
	v_fmac_f32_e32 v5, v10, v4
	s_lshl_b64 s[8:9], s[8:9], 2
	v_mov_b32_e32 v4, v6
	v_pk_mul_f32 v[6:7], v[2:3], v[6:7]
	s_add_u32 s8, s19, s8
	v_pk_mul_f32 v[6:7], v[0:1], v[6:7]
	v_pk_fma_f32 v[0:1], v[2:3], v[4:5], v[0:1]
	s_addc_u32 s9, s30, s9
	v_mov_b32_e32 v7, v1
	global_store_dwordx2 v84, v[6:7], s[8:9]
	s_branch .LBB0_693
